# v28: RWKV scans: LDS stores that are ready at the start of the per-token-operand segment are issued before its VALU block (overlap LDS drain with VALU), passes A and B
# baseline (speedup 1.0000x reference)
; __device__ __forceinline__ unsigned pk2(float lo, float hi) { const f32x2_cv v = {lo, hi}; const bf16x2_cv b = __builtin_convertvector(v, bf16x2_cv); return __builtin_bit_cast(unsigned, b); }
; template <bool PA> ...
;     ...
;             {
;                 const f32x4_t c0 = *(const f32x4_t*)(cumb + j * 64 + c8), c1 = *(const f32x4_t*)(cumb + j * 64 + c8 + 4);
;                 float ah[8], bh[8], kh[8], rh[8];
; #pragma unroll
;                 for (int e = 0; e < 8; ++e) { const float cu = e < 4 ? c0[e & 3] : c1[e & 3]; const float Wt = __expf(cu), iW = __expf(-cu), Wm1 = __expf(cu - lw[e]);
;                     ah[e] = kk[e] * Wm1; bh[e] = -(kk[e] * av[e]) * iW; kh[e] = kd[e] * iW; rh[e] = rv[e] * Wt;
;                     if (j == 63) wc[c8 + e] = Wt; }
;                 u32x4_t w;
;                 w.x = pk2(ah[0], ah[1]); w.y = pk2(ah[2], ah[3]); w.z = pk2(ah[4], ah[5]); w.w = pk2(ah[6], ah[7]); *(u32x4_t*)(MAT(0) + j * 72 + c8) = w;
;                 u32x4_t wb, wk;
;                 wb.x = pk2(bh[0], bh[1]); wb.y = pk2(bh[2], bh[3]); wb.z = pk2(bh[4], bh[5]); wb.w = pk2(bh[6], bh[7]); *(u32x4_t*)(MAT(1) + j * 72 + c8) = wb;
;                 wk.x = pk2(kh[0], kh[1]); wk.y = pk2(kh[2], kh[3]); wk.z = pk2(kh[4], kh[5]); wk.w = pk2(kh[6], kh[7]); *(u32x4_t*)(MAT(2) + j * 72 + c8) = wk;
;                 w.x = pk2(rh[0], rh[1]); w.y = pk2(rh[2], rh[3]); w.z = pk2(rh[4], rh[5]); w.w = pk2(rh[6], rh[7]); *(u32x4_t*)(MAT(3) + j * 72 + c8) = w;
;                 { const unsigned wba[4] = {wb.x, wb.y, wb.z, wb.w}, wka[4] = {wk.x, wk.y, wk.z, wk.w}, wva[4] = {vraw.x, vraw.y, vraw.z, vraw.w};
; #pragma unroll
;                   for (int q = 0; q < 4; ++q) { bf16* d4 = MAT(4) + (c8 + 2 * q) * 72 + j; bf16* d5 = MAT(5) + (c8 + 2 * q) * 72 + j; bf16* d6 = MAT(6) + (c8 + 2 * q) * 72 + j;
;                       d4[0] = (bf16)(wba[q] & 0xffffu); d4[72] = (bf16)(wba[q] >> 16); d5[0] = (bf16)(wka[q] & 0xffffu); d5[72] = (bf16)(wka[q] >> 16); d6[0] = (bf16)(wva[q] & 0xffffu); d6[72] = (bf16)(wva[q] >> 16); } }
;                 if (haveT) *(u32x4_t*)(MAT(9) + j * 72 + c8) = tld;
;                 st_rm(MAT(7), Sacc, mt, ntb, r16, kq);
.LBB0_152:
	s_or_b64 exec, exec, s[0:1]
	s_nop 0
	ds_write_b16 v117, v14 offset:55296
	ds_write_b16_d16_hi v117, v14 offset:55440
	ds_write_b16 v117, v15 offset:55584
	ds_write_b16_d16_hi v117, v15 offset:55728
	ds_write_b16 v176, v16 offset:55872
	ds_write_b16_d16_hi v176, v16 offset:56016
	ds_write_b16 v176, v17 offset:56160
	ds_write_b16_d16_hi v176, v17 offset:56304
	ds_write_b128 v101, v[10:13]
	v_cvt_pk_bf16_f32 v11, v6, v7
	v_cvt_pk_bf16_f32 v10, v8, v9
	s_nop 1
	v_mov_b32_dpp v200, v11 quad_perm:[1,0,3,2] row_mask:0xf bank_mask:0xf
	v_add_u32_e32 v177, v194, v87
	v_perm_b32 v200, v200, v11, v195
	ds_write_b32 v177, v200 offset:64512
	s_nop 1
	v_mov_b32_dpp v200, v10 quad_perm:[1,0,3,2] row_mask:0xf bank_mask:0xf
	v_perm_b32 v200, v200, v10, v195
	ds_write_b32 v177, v200 offset:64800
	v_cvt_pk_bf16_f32 v11, v2, v3
	v_cvt_pk_bf16_f32 v10, v4, v5
	s_nop 1
	v_mov_b32_dpp v200, v11 quad_perm:[1,0,3,2] row_mask:0xf bank_mask:0xf
	v_perm_b32 v200, v200, v11, v195
	ds_write_b32 v177, v200 offset:64544
	s_nop 1
	v_mov_b32_dpp v200, v10 quad_perm:[1,0,3,2] row_mask:0xf bank_mask:0xf
	v_perm_b32 v200, v200, v10, v195
	ds_write_b32 v177, v200 offset:64832
	v_lshlrev_b64 v[34:35], 10, v[80:81]
	v_add_f32_e32 v80, v149, v150
	v_max_f32_e32 v80, 0x179abe15, v80
	v_sub_f32_e32 v25, v33, v25
	v_rsq_f32_e32 v80, v80
	v_mul_f32_e32 v25, 0x3fb8aa3b, v25
	v_sub_f32_e32 v24, v32, v24
	v_exp_f32_e32 v25, v25
	v_mul_f32_e32 v24, 0x3fb8aa3b, v24
	v_sub_f32_e32 v23, v31, v23
	v_exp_f32_e32 v24, v24
	v_mul_f32_e32 v23, 0x3fb8aa3b, v23
	v_exp_f32_e32 v23, v23
	v_mul_f32_e32 v81, v145, v80
	v_mul_f32_e32 v145, 0xbfb8aa3b, v33
	v_mul_f32_e32 v25, v81, v25
	v_mul_f32_e64 v33, v81, -v40
	v_mul_f32_e32 v81, v144, v80
	v_mul_f32_e32 v40, v164, v143
	v_mul_f32_e32 v143, 0xbfb8aa3b, v32
	v_mul_f32_e32 v24, v81, v24
	v_mul_f32_e64 v32, v81, -v39
	v_mul_f32_e32 v81, v142, v80
	v_sub_f32_e32 v22, v30, v22
	v_mul_f32_e32 v39, v161, v141
	v_mul_f32_e32 v141, 0xbfb8aa3b, v31
	v_mul_f32_e32 v23, v81, v23
	v_mul_f32_e64 v31, v81, -v38
	v_mul_f32_e32 v81, v158, v139
	v_mul_f32_e32 v139, v140, v80
	v_mul_f32_e32 v140, 0xbfb8aa3b, v30
	v_mul_f32_e32 v22, 0x3fb8aa3b, v22
	v_exp_f32_e32 v140, v140
	v_exp_f32_e32 v22, v22
	v_mul_f32_e64 v30, v139, -v163
	v_sub_f32_e32 v21, v29, v21
	v_mul_f32_e32 v30, v30, v140
	v_mul_f32_e32 v22, v139, v22
	v_mul_f32_e32 v139, v165, v140
	v_mul_f32_e32 v140, 0xbfb8aa3b, v29
	v_mul_f32_e32 v21, 0x3fb8aa3b, v21
	v_exp_f32_e32 v140, v140
	v_exp_f32_e32 v21, v21
	v_mul_f32_e32 v138, v138, v80
	v_mul_f32_e64 v29, v138, -v159
	v_sub_f32_e32 v20, v28, v20
	v_mul_f32_e32 v21, v138, v21
	v_mul_f32_e32 v29, v29, v140
	v_mul_f32_e32 v138, v160, v140
	v_mul_f32_e32 v140, 0xbfb8aa3b, v28
	v_mul_f32_e32 v20, 0x3fb8aa3b, v20
	v_exp_f32_e32 v140, v140
	v_exp_f32_e32 v20, v20
	v_mul_f32_e32 v136, v136, v80
	v_sub_f32_e32 v19, v27, v19
	v_sub_f32_e32 v18, v26, v18
	v_mul_f32_e64 v28, v136, -v155
	v_mul_f32_e32 v19, 0x3fb8aa3b, v19
	v_mul_f32_e32 v18, 0x3fb8aa3b, v18
	v_mul_f32_e32 v20, v136, v20
	v_mul_f32_e32 v28, v28, v140
	v_mul_f32_e32 v136, v156, v140
	v_mul_f32_e32 v134, v134, v80
	v_mul_f32_e32 v140, 0xbfb8aa3b, v27
	v_exp_f32_e32 v19, v19
	v_mul_f32_e32 v80, v132, v80
	v_mul_f32_e32 v132, 0xbfb8aa3b, v26
	v_exp_f32_e32 v18, v18
	v_exp_f32_e32 v145, v145
	v_exp_f32_e32 v143, v143
	v_exp_f32_e32 v141, v141
	v_exp_f32_e32 v140, v140
	v_exp_f32_e32 v132, v132
	v_mul_f32_e32 v19, v134, v19
	v_mul_f32_e64 v27, v134, -v152
	v_mul_f32_e32 v18, v80, v18
	v_mul_f32_e64 v26, v80, -v148
	v_mul_f32_e32 v33, v33, v145
	v_mul_f32_e32 v37, v37, v145
	v_mul_f32_e32 v32, v32, v143
	v_mul_f32_e32 v36, v36, v143
	v_mul_f32_e32 v31, v31, v141
	v_mul_f32_e32 v38, v162, v141
	v_mul_f32_e32 v137, v157, v137
	v_mul_f32_e32 v135, v154, v135
	v_mul_f32_e32 v133, v147, v133
	v_mul_f32_e32 v27, v27, v140
	v_mul_f32_e32 v134, v153, v140
	v_mul_f32_e32 v131, v146, v131
	v_mul_f32_e32 v26, v26, v132
	v_mul_f32_e32 v80, v151, v132
	v_mul_f32_e32 v0, v41, v0
	v_cvt_pk_bf16_f32 v18, v18, v19
	v_cvt_pk_bf16_f32 v19, v20, v21
	v_cvt_pk_bf16_f32 v20, v22, v23
	v_cvt_pk_bf16_f32 v21, v24, v25
	ds_write_b128 v91, v[18:21]
	v_cvt_pk_bf16_f32 v18, v26, v27
	v_cvt_pk_bf16_f32 v19, v28, v29
	v_cvt_pk_bf16_f32 v20, v30, v31
	v_cvt_pk_bf16_f32 v21, v32, v33
	v_cvt_pk_bf16_f32 v22, v80, v134
	v_cvt_pk_bf16_f32 v23, v136, v138
	v_cvt_pk_bf16_f32 v24, v139, v38
	v_cvt_pk_bf16_f32 v25, v36, v37
	v_cvt_pk_bf16_f32 v26, v0, v131
	v_cvt_pk_bf16_f32 v27, v133, v135
	v_cvt_pk_bf16_f32 v28, v137, v81
	v_cvt_pk_bf16_f32 v29, v39, v40
	ds_write_b128 v91, v[18:21] offset:9216
	ds_write_b128 v91, v[22:25] offset:18432
	ds_write_b128 v91, v[26:29] offset:27648
	ds_write_b16 v117, v18 offset:36864
	ds_write_b16_d16_hi v117, v18 offset:37008
	ds_write_b16 v117, v22 offset:46080
	ds_write_b16_d16_hi v117, v22 offset:46224
	s_nop 0
	ds_write_b16 v117, v19 offset:37152
	ds_write_b16_d16_hi v117, v19 offset:37296
	ds_write_b16 v117, v23 offset:46368
	ds_write_b16_d16_hi v117, v23 offset:46512
	ds_write_b16 v176, v20 offset:37440
	ds_write_b16_d16_hi v176, v20 offset:37584
	ds_write_b16 v176, v24 offset:46656
	ds_write_b16_d16_hi v176, v24 offset:46800
	ds_write_b16 v176, v21 offset:37728
	ds_write_b16_d16_hi v176, v21 offset:37872
	ds_write_b16 v176, v25 offset:46944
	ds_write_b16_d16_hi v176, v25 offset:47088
	s_waitcnt lgkmcnt(0)
	s_barrier
; template <bool PA> ...
;     ...
;             tmp[0] = z4; tmp[1] = z4; mm2(tmp, MAT(0), MAT(2), mt, ntb, r16, kq);
; #pragma unroll
;             for (int i = 0; i < 2; ++i)
; #pragma unroll
;                 for (int e = 0; e < 4; ++e) { const int t = 16 * mt + 4 * kq + e, s = 16 * (ntb + i) + r16; tmp[i][e] = (s < t) ? tmp[i][e] : 0.f; }
;             st_rm(MAT(10), tmp, mt, ntb, r16, kq);
;             f32x4_t X2acc[2]; X2acc[0] = z4; X2acc[1] = z4;
;             if (PA) mm2(X2acc, MAT(0), MAT(12), mt, ntb, r16, kq);
;             if (!PA) {
;             tmp[0] = z4; tmp[1] = z4; mm2(tmp, MAT(3), MAT(1), mt, ntb, r16, kq);
; #pragma unroll
;             for (int i = 0; i < 2; ++i)
; #pragma unroll
;                 for (int e = 0; e < 4; ++e) { const int t = 16 * mt + 4 * kq + e, s = 16 * (ntb + i) + r16; tmp[i][e] = (s <= t) ? tmp[i][e] : 0.f; }
;             st_rm(MAT(11), tmp, mt, ntb, r16, kq);
;             tmp[0] = z4; tmp[1] = z4; mm2(tmp, MAT(3), MAT(2), mt, ntb, r16, kq);
; #pragma unroll
;             for (int i = 0; i < 2; ++i)
; #pragma unroll
;                 for (int e = 0; e < 4; ++e) { const int t = 16 * mt + 4 * kq + e, s = 16 * (ntb + i) + r16; tmp[i][e] = (s <= t) ? tmp[i][e] : 0.f; }
;             st_rm(MAT(12), tmp, mt, ntb, r16, kq);
;             }
;             Xacc[0] = z4; Xacc[1] = z4; mm2(Xacc, MAT(0), MAT(7), mt, ntb, r16, kq);
;             Yacc[0] = z4; Yacc[1] = z4; if (!PA) mm2(Yacc, MAT(3), MAT(7), mt, ntb, r16, kq);
;             __syncthreads();
	ds_read_b128 v[178:181], v92
	ds_read_b128 v[182:185], v89 offset:18432
	ds_read_b128 v[186:189], v89 offset:20736
	ds_read_b128 v[190:193], v92 offset:64
	ds_read_b128 v[204:207], v89 offset:18496
	ds_read_b128 v[208:211], v89 offset:20800
	ds_read_b128 v[212:215], v92 offset:27648
	ds_read_b128 v[216:219], v89 offset:9216
	ds_read_b128 v[220:223], v89 offset:11520
	ds_read_b128 v[224:227], v92 offset:27712
	s_nop 0
	s_nop 0
	s_nop 0
	s_waitcnt lgkmcnt(8)
	v_mfma_f32_16x16x32_bf16 v[14:17], v[178:181], v[182:185], 0
	ds_read_b128 v[182:185], v89 offset:9280
	s_add_i32 s12, s12, 1
	s_add_i32 s18, s18, -1
	v_lshl_add_u64 v[78:79], v[78:79], 0, s[34:35]
	s_waitcnt lgkmcnt(8)
	v_mfma_f32_16x16x32_bf16 v[10:13], v[178:181], v[186:189], 0
	ds_read_b128 v[178:181], v89 offset:11584
	ds_read_b128 v[186:189], v92 offset:27648
	s_nop 0
	s_nop 0
	s_cmp_ge_i32 s12, s13
	s_waitcnt lgkmcnt(8)
	v_mfma_f32_16x16x32_bf16 v[14:17], v[190:193], v[204:207], v[14:17]
	ds_read_b128 v[204:207], v89 offset:18432
	s_nop 0
	s_waitcnt lgkmcnt(8)
	v_mfma_f32_16x16x32_bf16 v[10:13], v[190:193], v[208:211], v[10:13]
	ds_read_b128 v[190:193], v89 offset:20736
	ds_read_b128 v[208:211], v92 offset:27712
	s_nop 4
	v_cndmask_b32_e64 v0, 0, v14, s[62:63]
	v_cndmask_b32_e64 v14, v15, 0, s[64:65]
	v_cndmask_b32_e64 v15, 0, v16, s[66:67]
	v_cndmask_b32_e64 v16, 0, v17, s[68:69]
	v_cndmask_b32_e64 v10, 0, v10, s[70:71]
	v_cndmask_b32_e64 v11, v11, 0, s[72:73]
	v_cvt_pk_bf16_f32 v0, v0, v14
	v_cndmask_b32_e64 v12, 0, v12, s[74:75]
	v_cndmask_b32_e64 v13, 0, v13, s[76:77]
	v_cvt_pk_bf16_f32 v14, v15, v16
	s_nop 1
	v_mov_b32_dpp v200, v0 quad_perm:[1,0,3,2] row_mask:0xf bank_mask:0xf
	v_add_u32_e32 v177, v194, v102
	v_perm_b32 v200, v200, v0, v195
	ds_write_b32 v177, v200
	s_nop 1
	v_mov_b32_dpp v200, v14 quad_perm:[1,0,3,2] row_mask:0xf bank_mask:0xf
	v_perm_b32 v200, v200, v14, v195
	ds_write_b32 v177, v200 offset:288
	v_cvt_pk_bf16_f32 v0, v10, v11
	v_cvt_pk_bf16_f32 v10, v12, v13
	s_nop 1
	v_mov_b32_dpp v200, v0 quad_perm:[1,0,3,2] row_mask:0xf bank_mask:0xf
	v_perm_b32 v200, v200, v0, v195
	ds_write_b32 v177, v200 offset:32
	s_nop 1
	v_mov_b32_dpp v200, v10 quad_perm:[1,0,3,2] row_mask:0xf bank_mask:0xf
	v_perm_b32 v200, v200, v10, v195
	ds_write_b32 v177, v200 offset:320
	s_nop 0
	s_nop 0
	s_nop 0
	s_waitcnt lgkmcnt(0)
	v_mfma_f32_16x16x32_bf16 v[14:17], v[212:215], v[216:219], 0
	ds_read_b128 v[216:219], v89 offset:18496
	s_waitcnt lgkmcnt(1)
	v_mfma_f32_16x16x32_bf16 v[10:13], v[212:215], v[220:223], 0
	ds_read_b128 v[212:215], v89 offset:20800
	ds_read_b128 v[220:223], v92
	s_nop 0
	s_nop 0
	s_waitcnt lgkmcnt(3)
	v_mfma_f32_16x16x32_bf16 v[14:17], v[224:227], v[182:185], v[14:17]
	ds_read_b128 v[182:185], v89 offset:64512
	s_nop 0
	s_waitcnt lgkmcnt(4)
	v_mfma_f32_16x16x32_bf16 v[10:13], v[224:227], v[178:181], v[10:13]
	ds_read_b128 v[178:181], v105
	ds_read_b128 v[224:227], v92 offset:64
	s_nop 4
	v_cndmask_b32_e64 v0, v14, 0, s[64:65]
	v_cndmask_b32_e64 v14, v15, 0, s[78:79]
	v_cndmask_b32_e64 v15, v16, 0, s[80:81]
	v_cndmask_b32_e64 v16, v17, 0, s[82:83]
	v_cndmask_b32_e64 v10, v10, 0, s[72:73]
	v_cndmask_b32_e64 v11, v11, 0, s[84:85]
	v_cvt_pk_bf16_f32 v0, v0, v14
	v_cndmask_b32_e64 v12, v12, 0, s[86:87]
	v_cndmask_b32_e64 v13, v13, 0, s[88:89]
	v_cvt_pk_bf16_f32 v14, v15, v16
	s_nop 1
	v_mov_b32_dpp v200, v0 quad_perm:[1,0,3,2] row_mask:0xf bank_mask:0xf
	v_add_u32_e32 v177, v194, v103
	v_perm_b32 v200, v200, v0, v195
	ds_write_b32 v177, v200
	s_nop 1
	v_mov_b32_dpp v200, v14 quad_perm:[1,0,3,2] row_mask:0xf bank_mask:0xf
	v_perm_b32 v200, v200, v14, v195
	ds_write_b32 v177, v200 offset:288
	v_cvt_pk_bf16_f32 v0, v10, v11
	v_cvt_pk_bf16_f32 v10, v12, v13
	s_nop 1
	v_mov_b32_dpp v200, v0 quad_perm:[1,0,3,2] row_mask:0xf bank_mask:0xf
	v_perm_b32 v200, v200, v0, v195
	ds_write_b32 v177, v200 offset:32
	s_nop 1
	v_mov_b32_dpp v200, v10 quad_perm:[1,0,3,2] row_mask:0xf bank_mask:0xf
	v_perm_b32 v200, v200, v10, v195
	ds_write_b32 v177, v200 offset:320
	s_nop 0
	s_nop 0
	s_nop 0
	s_waitcnt lgkmcnt(0)
	v_mfma_f32_16x16x32_bf16 v[14:17], v[186:189], v[204:207], 0
	ds_read_b128 v[204:207], v92 offset:27648
	s_waitcnt lgkmcnt(1)
	v_mfma_f32_16x16x32_bf16 v[10:13], v[186:189], v[190:193], 0
	s_nop 0
	s_nop 0
	s_waitcnt lgkmcnt(1)
	v_mfma_f32_16x16x32_bf16 v[14:17], v[208:211], v[216:219], v[14:17]
	s_nop 0
	s_waitcnt lgkmcnt(1)
	v_mfma_f32_16x16x32_bf16 v[10:13], v[208:211], v[212:215], v[10:13]
	s_nop 4
	v_cndmask_b32_e64 v0, v14, 0, s[64:65]
	v_cndmask_b32_e64 v14, v15, 0, s[78:79]
	v_cndmask_b32_e64 v15, v16, 0, s[80:81]
	v_cndmask_b32_e64 v16, v17, 0, s[82:83]
	v_cndmask_b32_e64 v10, v10, 0, s[72:73]
	v_cndmask_b32_e64 v11, v11, 0, s[84:85]
	v_cvt_pk_bf16_f32 v0, v0, v14
	v_cndmask_b32_e64 v12, v12, 0, s[86:87]
	v_cndmask_b32_e64 v13, v13, 0, s[88:89]
	v_cvt_pk_bf16_f32 v14, v15, v16
	s_nop 1
	v_mov_b32_dpp v200, v0 quad_perm:[1,0,3,2] row_mask:0xf bank_mask:0xf
	v_add_u32_e32 v177, v194, v104
	v_perm_b32 v200, v200, v0, v195
	ds_write_b32 v177, v200
	s_nop 1
	v_mov_b32_dpp v200, v14 quad_perm:[1,0,3,2] row_mask:0xf bank_mask:0xf
	v_perm_b32 v200, v200, v14, v195
	ds_write_b32 v177, v200 offset:288
	v_cvt_pk_bf16_f32 v0, v10, v11
	v_cvt_pk_bf16_f32 v10, v12, v13
	s_nop 1
	v_mov_b32_dpp v200, v0 quad_perm:[1,0,3,2] row_mask:0xf bank_mask:0xf
	v_perm_b32 v200, v200, v0, v195
	ds_write_b32 v177, v200 offset:32
	s_nop 1
	v_mov_b32_dpp v200, v10 quad_perm:[1,0,3,2] row_mask:0xf bank_mask:0xf
	v_perm_b32 v200, v200, v10, v195
	ds_write_b32 v177, v200 offset:320
	s_nop 0
	s_nop 0
	s_nop 0
	s_nop 0
	ds_read_b128 v[30:33], v89 offset:64576
	ds_read_b128 v[36:39], v106
	s_waitcnt lgkmcnt(2)
	v_mfma_f32_16x16x32_bf16 v[18:21], v[220:223], v[182:185], 0
	s_waitcnt lgkmcnt(2)
	v_mfma_f32_16x16x32_bf16 v[10:13], v[220:223], v[178:181], 0
	s_waitcnt lgkmcnt(1)
	v_mfma_f32_16x16x32_bf16 v[18:21], v[224:227], v[30:33], v[18:21]
	s_waitcnt lgkmcnt(0)
	v_mfma_f32_16x16x32_bf16 v[10:13], v[224:227], v[36:39], v[10:13]
	s_nop 0
	s_waitcnt lgkmcnt(0)
	v_mfma_f32_16x16x32_bf16 v[14:17], v[204:207], v[182:185], 0
	v_mfma_f32_16x16x32_bf16 v[22:25], v[204:207], v[178:181], 0
	ds_read_b128 v[26:29], v92 offset:27712
	s_waitcnt lgkmcnt(0)
	s_barrier
; template <bool PA> ...
;     ...
;             mm2(Xacc, MAT(10), MAT(6), mt, ntb, r16, kq);
;             st_tr(MAT(7), Xacc, mt, ntb, r16, kq);
;             if (PA) st_tr(MAT(11), X2acc, mt, ntb, r16, kq);
;             __syncthreads();
;             tmp[0] = z4; tmp[1] = z4; mm2(tmp, Tm, MAT(7), mt, ntb, r16, kq);
;             st_tr(MAT(8), tmp, mt, ntb, r16, kq);
;             if (PA) { tmp[0] = z4; tmp[1] = z4; mm2(tmp, MAT(3), MAT(11), mt, ntb, r16, kq); st_tr(MAT(12), tmp, mt, ntb, r16, kq); }
;             __syncthreads();
;             if (!PA) { mm2(Yacc, MAT(11), MAT(8), mt, ntb, r16, kq); mm2(Yacc, MAT(12), MAT(6), mt, ntb, r16, kq);
;             st_rm(MAT(7), Yacc, mt, ntb, r16, kq); }
;             if (PA) mm2(S2acc, MAT(12), MAT(4), mt, ntb, r16, kq);
;             mm2(Sacc, MAT(8), MAT(4), mt, ntb, r16, kq); mm2(Sacc, MAT(6), MAT(5), mt, ntb, r16, kq);
; #pragma unroll
;             for (int i = 0; i < 2; ++i) { const float wk = wc[16 * (ntb + i) + r16];
; #pragma unroll
;                 for (int e = 0; e < 4; ++e) { Sacc[i][e] *= wk; S2acc[i][e] *= wk; } }
;             __syncthreads();
;             if (!PA) { const size_t orow = cbase + (d ? 63 - j : j); *(u32x4_t*)(Op + orow * 1024 + hc8) = *(const u32x4_t*)(MAT(7) + j * 72 + c8); }
	ds_read_b128 v[178:181], v107
	ds_read_b128 v[182:185], v89 offset:55296
	ds_read_b128 v[186:189], v89 offset:57600
	ds_read_b128 v[190:193], v107 offset:64
	ds_read_b128 v[204:207], v89 offset:55360
	ds_read_b128 v[208:211], v89 offset:57664
	v_mfma_f32_16x16x32_bf16 v[14:17], v[26:29], v[30:33], v[14:17]
	v_mfma_f32_16x16x32_bf16 v[22:25], v[26:29], v[36:39], v[22:25]
	s_nop 0
	s_nop 0
	s_waitcnt lgkmcnt(4)
	v_mfma_f32_16x16x32_bf16 v[18:21], v[178:181], v[182:185], v[18:21]
	s_nop 0
	s_waitcnt lgkmcnt(3)
	v_mfma_f32_16x16x32_bf16 v[10:13], v[178:181], v[186:189], v[10:13]
	s_nop 0
	s_nop 0
	s_waitcnt lgkmcnt(1)
	v_mfma_f32_16x16x32_bf16 v[18:21], v[190:193], v[204:207], v[18:21]
	s_nop 0
	s_waitcnt lgkmcnt(0)
	v_mfma_f32_16x16x32_bf16 v[10:13], v[190:193], v[208:211], v[10:13]
	s_nop 4
	v_cvt_pk_bf16_f32 v18, v18, v19
	v_cvt_pk_bf16_f32 v19, v20, v21
	ds_write_b64 v108, v[18:19] offset:64512
	v_cvt_pk_bf16_f32 v10, v10, v11
	v_cvt_pk_bf16_f32 v11, v12, v13
	ds_write_b64 v109, v[10:11]
	s_waitcnt lgkmcnt(0)
	s_barrier
	ds_read_b128 v[178:181], v110
	ds_read_b128 v[182:185], v89 offset:64512
	ds_read_b128 v[186:189], v105
	ds_read_b128 v[190:193], v110 offset:64
	ds_read_b128 v[204:207], v89 offset:64576
	ds_read_b128 v[208:211], v106
	s_nop 0
	s_nop 0
	s_nop 0
	s_waitcnt lgkmcnt(4)
	v_mfma_f32_16x16x32_bf16 v[18:21], v[178:181], v[182:185], 0
	s_waitcnt lgkmcnt(3)
	v_mfma_f32_16x16x32_bf16 v[10:13], v[178:181], v[186:189], 0
	s_nop 0
	s_nop 0
	s_waitcnt lgkmcnt(1)
	v_mfma_f32_16x16x32_bf16 v[18:21], v[190:193], v[204:207], v[18:21]
	s_nop 0
	s_waitcnt lgkmcnt(0)
	v_mfma_f32_16x16x32_bf16 v[10:13], v[190:193], v[208:211], v[10:13]
	v_mov_b32_e32 v26, v190
	v_mov_b32_e32 v27, v191
	v_mov_b32_e32 v28, v192
	v_mov_b32_e32 v29, v193
	v_mov_b32_e32 v30, v208
	v_mov_b32_e32 v31, v209
	v_mov_b32_e32 v32, v210
	v_mov_b32_e32 v33, v211
	s_nop 4
	v_cvt_pk_bf16_f32 v18, v18, v19
	v_cvt_pk_bf16_f32 v19, v20, v21
	ds_write_b64 v111, v[18:19]
	v_cvt_pk_bf16_f32 v10, v10, v11
	v_cvt_pk_bf16_f32 v11, v12, v13
	ds_write_b64 v111, v[10:11] offset:2304
	s_waitcnt lgkmcnt(0)
	s_barrier
	ds_read_b128 v[178:181], v112
	ds_read_b128 v[182:185], v113
	ds_read_b128 v[186:189], v113 offset:2304
	ds_read_b128 v[190:193], v112 offset:64
	ds_read_b128 v[204:207], v113 offset:64
	ds_read_b128 v[208:211], v113 offset:2368
	ds_read_b128 v[212:215], v114
	ds_read_b128 v[216:219], v89 offset:55296
	ds_read_b128 v[220:223], v89 offset:57600
	ds_read_b128 v[224:227], v114 offset:64
	s_nop 0
	s_nop 0
	s_waitcnt lgkmcnt(8)
	v_mfma_f32_16x16x32_bf16 v[14:17], v[178:181], v[182:185], v[14:17]
	ds_read_b128 v[182:185], v89 offset:55360
	s_nop 0
	s_waitcnt lgkmcnt(8)
	v_mfma_f32_16x16x32_bf16 v[10:13], v[178:181], v[186:189], v[22:25]
	ds_read_b128 v[178:181], v89 offset:57664
	ds_read_b128 v[186:189], v115
	s_nop 0
	s_nop 1
	s_nop 0
	s_waitcnt lgkmcnt(8)
	v_mfma_f32_16x16x32_bf16 v[14:17], v[190:193], v[204:207], v[14:17]
	ds_read_b128 v[204:207], v89 offset:36864
	s_nop 0
	s_waitcnt lgkmcnt(8)
	v_mfma_f32_16x16x32_bf16 v[10:13], v[190:193], v[208:211], v[10:13]
	ds_read_b128 v[190:193], v89 offset:39168
	ds_read_b128 v[208:211], v115 offset:64
	s_nop 0
	s_nop 0
	s_waitcnt lgkmcnt(8)
	v_mfma_f32_16x16x32_bf16 v[14:17], v[212:215], v[216:219], v[14:17]
	ds_read_b128 v[216:219], v89 offset:36928
	s_nop 0
	s_waitcnt lgkmcnt(8)
	v_mfma_f32_16x16x32_bf16 v[10:13], v[212:215], v[220:223], v[10:13]
	ds_read_b128 v[212:215], v89 offset:39232
	ds_read_b128 v[220:223], v92 offset:55296
	s_nop 0
	s_nop 0
	s_waitcnt lgkmcnt(8)
	v_mfma_f32_16x16x32_bf16 v[14:17], v[224:227], v[182:185], v[14:17]
	ds_read_b128 v[182:185], v89 offset:46080
	s_nop 0
	s_waitcnt lgkmcnt(8)
	v_mfma_f32_16x16x32_bf16 v[10:13], v[224:227], v[178:181], v[10:13]
	v_mov_b32_e32 v18, v224
	v_mov_b32_e32 v19, v225
	v_mov_b32_e32 v20, v226
	v_mov_b32_e32 v21, v227
	v_mov_b32_e32 v22, v178
	v_mov_b32_e32 v23, v179
	v_mov_b32_e32 v24, v180
	v_mov_b32_e32 v25, v181
	ds_read_b128 v[178:181], v89 offset:48384
	ds_read_b128 v[224:227], v92 offset:55360
	s_nop 4
	v_cvt_pk_bf16_f32 v0, v14, v15
	v_cvt_pk_bf16_f32 v14, v16, v17
	s_nop 1
	v_mov_b32_dpp v200, v0 quad_perm:[1,0,3,2] row_mask:0xf bank_mask:0xf
	v_add_u32_e32 v177, v194, v87
	v_perm_b32 v200, v200, v0, v195
	ds_write_b32 v177, v200 offset:64512
	s_nop 1
	v_mov_b32_dpp v200, v14 quad_perm:[1,0,3,2] row_mask:0xf bank_mask:0xf
	v_perm_b32 v200, v200, v14, v195
	ds_write_b32 v177, v200 offset:64800
	v_cvt_pk_bf16_f32 v0, v10, v11
	v_cvt_pk_bf16_f32 v10, v12, v13
	s_nop 1
	v_mov_b32_dpp v200, v0 quad_perm:[1,0,3,2] row_mask:0xf bank_mask:0xf
	v_perm_b32 v200, v200, v0, v195
	ds_write_b32 v177, v200 offset:64544
	s_nop 1
	v_mov_b32_dpp v200, v10 quad_perm:[1,0,3,2] row_mask:0xf bank_mask:0xf
	v_perm_b32 v200, v200, v10, v195
	ds_write_b32 v177, v200 offset:64832
	s_nop 0
	s_nop 0
	s_waitcnt lgkmcnt(0)
	v_mfma_f32_16x16x32_bf16 v[6:9], v[186:189], v[204:207], v[6:9]
	ds_read_b128 v[204:207], v89 offset:46144
	s_nop 0
	s_waitcnt lgkmcnt(1)
	v_mfma_f32_16x16x32_bf16 v[2:5], v[186:189], v[190:193], v[2:5]
	ds_read_b128 v[186:189], v89 offset:48448
	s_nop 0
	s_nop 0
	s_waitcnt lgkmcnt(2)
	v_mfma_f32_16x16x32_bf16 v[6:9], v[208:211], v[216:219], v[6:9]
	s_nop 0
	s_waitcnt lgkmcnt(2)
	v_mfma_f32_16x16x32_bf16 v[2:5], v[208:211], v[212:215], v[2:5]
	s_nop 0
	s_nop 0
	s_waitcnt lgkmcnt(2)
	v_mfma_f32_16x16x32_bf16 v[6:9], v[220:223], v[182:185], v[6:9]
	s_nop 0
	s_waitcnt lgkmcnt(2)
	v_mfma_f32_16x16x32_bf16 v[2:5], v[220:223], v[178:181], v[2:5]
	s_nop 0
	s_nop 0
	ds_read_b32 v0, v127
	s_waitcnt lgkmcnt(2)
	v_mfma_f32_16x16x32_bf16 v[6:9], v[224:227], v[204:207], v[6:9]
	s_nop 0
	s_waitcnt lgkmcnt(0)
	v_mfma_f32_16x16x32_bf16 v[2:5], v[224:227], v[186:189], v[2:5]
	v_mov_b32_e32 v16, v188
	v_mov_b32_e32 v17, v189
	s_nop 4
	v_mul_f32_e64 v6, v6, v0
	v_mul_f32_e64 v7, v7, v0
	v_pk_mul_f32 v[8:9], v[8:9], v[0:1] op_sel_hi:[1,0]
	ds_read_b32 v0, v128
	s_waitcnt lgkmcnt(0)
	s_barrier
	ds_read_b128 v[10:13], v91 offset:64512
	v_pk_mul_f32 v[2:3], v[2:3], v[0:1] op_sel_hi:[1,0]
	v_pk_mul_f32 v[4:5], v[4:5], v[0:1] op_sel_hi:[1,0]
	v_lshl_add_u64 v[14:15], v[34:35], 1, v[76:77]
	s_waitcnt lgkmcnt(0)
	global_store_dwordx4 v[14:15], v[10:13], off
	s_cbranch_scc1 .LBB0_128

; template <bool PA> ...
;     ...
;             { const int c = tid & 63, sg = tid >> 6; float off = 0.f;
; #pragma unroll
;               for (int s = 0; s < 7; ++s) off += (s < sg) ? segtot[s * 64 + c] : 0.f;
; #pragma unroll
;               for (int i = 0; i < 8; ++i) cumb[(8 * sg + i) * 64 + c] += off; }
;             __syncthreads();
;             {
;                 const f32x4_t c0 = *(const f32x4_t*)(cumb + j * 64 + c8), c1 = *(const f32x4_t*)(cumb + j * 64 + c8 + 4);
;                 float ah[8], bh[8], kh[8], rh[8];
; #pragma unroll
;                 for (int e = 0; e < 8; ++e) { const float cu = e < 4 ? c0[e & 3] : c1[e & 3]; const float Wt = __expf(cu), iW = __expf(-cu), Wm1 = __expf(cu - lw[e]);
;                     ah[e] = kk[e] * Wm1; bh[e] = -(kk[e] * av[e]) * iW; kh[e] = kd[e] * iW; rh[e] = rv[e] * Wt;
;                     if (j == 63) wc[c8 + e] = Wt; }
;                 u32x4_t w;
;                 w.x = pk2(ah[0], ah[1]); w.y = pk2(ah[2], ah[3]); w.z = pk2(ah[4], ah[5]); w.w = pk2(ah[6], ah[7]); *(u32x4_t*)(MAT(0) + j * 72 + c8) = w;
;                 u32x4_t wb, wk;
;                 wb.x = pk2(bh[0], bh[1]); wb.y = pk2(bh[2], bh[3]); wb.z = pk2(bh[4], bh[5]); wb.w = pk2(bh[6], bh[7]); *(u32x4_t*)(MAT(1) + j * 72 + c8) = wb;
;                 wk.x = pk2(kh[0], kh[1]); wk.y = pk2(kh[2], kh[3]); wk.z = pk2(kh[4], kh[5]); wk.w = pk2(kh[6], kh[7]); *(u32x4_t*)(MAT(2) + j * 72 + c8) = wk;
;                 w.x = pk2(rh[0], rh[1]); w.y = pk2(rh[2], rh[3]); w.z = pk2(rh[4], rh[5]); w.w = pk2(rh[6], rh[7]); *(u32x4_t*)(MAT(3) + j * 72 + c8) = w;
;                 { const unsigned wba[4] = {wb.x, wb.y, wb.z, wb.w}, wka[4] = {wk.x, wk.y, wk.z, wk.w}, wva[4] = {vraw.x, vraw.y, vraw.z, vraw.w};
; #pragma unroll
;                   for (int q = 0; q < 4; ++q) { bf16* d4 = MAT(4) + (c8 + 2 * q) * 72 + j; bf16* d5 = MAT(5) + (c8 + 2 * q) * 72 + j; bf16* d6 = MAT(6) + (c8 + 2 * q) * 72 + j;
;                       d4[0] = (bf16)(wba[q] & 0xffffu); d4[72] = (bf16)(wba[q] >> 16); d5[0] = (bf16)(wka[q] & 0xffffu); d5[72] = (bf16)(wka[q] >> 16); d6[0] = (bf16)(wva[q] & 0xffffu); d6[72] = (bf16)(wva[q] >> 16); } }
;                 if (haveT) *(u32x4_t*)(MAT(9) + j * 72 + c8) = tld;
;                 st_rm(MAT(7), Sacc, mt, ntb, r16, kq);
;                 if (PA) st_rm(MAT(12), S2acc, mt, ntb, r16, kq);
.LBB0_215:
	s_or_b64 exec, exec, s[12:13]
	v_mov_b32_e32 v59, 0
	v_mov_b32_e32 v60, 0
	s_and_saveexec_b64 s[12:13], s[46:47]
	ds_read_b32 v60, v114 offset:256
	s_or_b64 exec, exec, s[12:13]
	s_and_saveexec_b64 s[12:13], s[48:49]
	ds_read_b32 v59, v114 offset:512
	s_or_b64 exec, exec, s[12:13]
	v_mov_b32_e32 v61, 0
	v_mov_b32_e32 v62, 0
	s_and_saveexec_b64 s[12:13], s[50:51]
	ds_read_b32 v62, v114 offset:768
	s_or_b64 exec, exec, s[12:13]
	s_and_saveexec_b64 s[12:13], s[52:53]
	ds_read_b32 v61, v114 offset:1024
	s_or_b64 exec, exec, s[12:13]
	v_mov_b32_e32 v63, 0
	v_mov_b32_e32 v64, 0
	s_and_saveexec_b64 s[12:13], s[54:55]
	ds_read_b32 v64, v114 offset:1280
	s_or_b64 exec, exec, s[12:13]
	s_and_saveexec_b64 s[12:13], s[56:57]
	ds_read_b32 v63, v114 offset:1536
	s_or_b64 exec, exec, s[12:13]
	s_waitcnt lgkmcnt(0)
	v_add_f32_e32 v58, v58, v60
	v_add_f32_e32 v58, v58, v59
	v_add_f32_e32 v58, v58, v62
	v_add_f32_e32 v58, v58, v61
	v_add_f32_e32 v60, v58, v64
	ds_read2st64_b32 v[58:59], v159 offset1:1
	v_add_f32_e32 v177, v60, v63
	ds_read2st64_b32 v[60:61], v159 offset0:2 offset1:3
	ds_read2st64_b32 v[62:63], v159 offset0:4 offset1:5
	ds_read2st64_b32 v[64:65], v159 offset0:6 offset1:7
	s_waitcnt lgkmcnt(3)
	v_add_f32_e32 v58, v177, v58
	v_add_f32_e32 v59, v177, v59
	ds_write2st64_b32 v159, v58, v59 offset1:1
	s_waitcnt lgkmcnt(3)
	v_add_f32_e32 v58, v177, v60
	v_add_f32_e32 v59, v177, v61
	ds_write2st64_b32 v159, v58, v59 offset0:2 offset1:3
	s_waitcnt lgkmcnt(3)
	v_add_f32_e32 v58, v177, v62
	v_add_f32_e32 v59, v177, v63
	ds_write2st64_b32 v159, v58, v59 offset0:4 offset1:5
	s_waitcnt lgkmcnt(3)
	v_add_f32_e32 v58, v177, v64
	v_add_f32_e32 v59, v177, v65
	ds_write2st64_b32 v159, v58, v59 offset0:6 offset1:7
	s_waitcnt lgkmcnt(0)
	s_barrier
	ds_read_b128 v[58:61], v112
	ds_read_b128 v[62:65], v112 offset:16
	s_waitcnt lgkmcnt(1)
	v_mul_f32_e32 v177, 0x3fb8aa3b, v58
	v_exp_f32_e32 v177, v177
	s_and_saveexec_b64 s[12:13], s[42:43]
	ds_write_b32 v115, v177
	s_or_b64 exec, exec, s[12:13]
	v_mul_f32_e32 v178, 0x3fb8aa3b, v59
	v_exp_f32_e32 v178, v178
	s_and_saveexec_b64 s[12:13], s[42:43]
	ds_write_b32 v115, v178 offset:4
	s_or_b64 exec, exec, s[12:13]
	v_mul_f32_e32 v179, 0x3fb8aa3b, v60
	v_exp_f32_e32 v179, v179
	s_and_saveexec_b64 s[12:13], s[42:43]
	ds_write_b32 v115, v179 offset:8
	s_or_b64 exec, exec, s[12:13]
	v_mul_f32_e32 v180, 0x3fb8aa3b, v61
	v_exp_f32_e32 v180, v180
	s_and_saveexec_b64 s[12:13], s[42:43]
	ds_write_b32 v115, v180 offset:12
	s_or_b64 exec, exec, s[12:13]
	s_waitcnt lgkmcnt(0)
	v_mul_f32_e32 v181, 0x3fb8aa3b, v62
	v_exp_f32_e32 v181, v181
	s_and_saveexec_b64 s[12:13], s[42:43]
	ds_write_b32 v115, v181 offset:16
	s_or_b64 exec, exec, s[12:13]
	v_mul_f32_e32 v182, 0x3fb8aa3b, v63
	v_exp_f32_e32 v182, v182
	s_and_saveexec_b64 s[12:13], s[42:43]
	ds_write_b32 v115, v182 offset:20
	s_or_b64 exec, exec, s[12:13]
	v_mul_f32_e32 v183, 0x3fb8aa3b, v64
	v_exp_f32_e32 v183, v183
	s_and_saveexec_b64 s[12:13], s[42:43]
	ds_write_b32 v115, v183 offset:24
	s_or_b64 exec, exec, s[12:13]
	v_mul_f32_e32 v184, 0x3fb8aa3b, v65
	v_exp_f32_e32 v184, v184
	s_and_saveexec_b64 s[12:13], s[42:43]
	ds_write_b32 v115, v184 offset:28
	s_or_b64 exec, exec, s[12:13]
	s_nop 0
	ds_write_b16 v154, v18 offset:55296
	ds_write_b16_d16_hi v154, v18 offset:55440
	ds_write_b16 v154, v19 offset:55584
	ds_write_b16_d16_hi v154, v19 offset:55728
	ds_write_b16 v185, v20 offset:55872
	ds_write_b16_d16_hi v185, v20 offset:56016
	ds_write_b16 v185, v21 offset:56160
	ds_write_b16_d16_hi v185, v21 offset:56304
	v_cvt_pk_bf16_f32 v18, v2, v3
	v_cvt_pk_bf16_f32 v19, v4, v5
	s_nop 1
	v_mov_b32_dpp v200, v18 quad_perm:[1,0,3,2] row_mask:0xf bank_mask:0xf
	v_add_u32_e32 v229, v194, v116
	v_perm_b32 v200, v200, v18, v195
	ds_write_b32 v229, v200 offset:64512
	s_nop 1
	v_mov_b32_dpp v228, v19 quad_perm:[1,0,3,2] row_mask:0xf bank_mask:0xf
	v_perm_b32 v228, v228, v19, v195
	ds_write_b32 v229, v228 offset:64800
	v_cvt_pk_bf16_f32 v18, v6, v7
	v_cvt_pk_bf16_f32 v0, v8, v0
	s_nop 1
	v_mov_b32_dpp v200, v18 quad_perm:[1,0,3,2] row_mask:0xf bank_mask:0xf
	v_perm_b32 v200, v200, v18, v195
	ds_write_b32 v229, v200 offset:64544
	s_nop 1
	v_mov_b32_dpp v228, v0 quad_perm:[1,0,3,2] row_mask:0xf bank_mask:0xf
	v_perm_b32 v228, v228, v0, v195
	ds_write_b32 v229, v228 offset:64832
	v_cvt_pk_bf16_f32 v0, v10, v11
	v_cvt_pk_bf16_f32 v18, v12, v13
	s_nop 1
	v_mov_b32_dpp v200, v0 quad_perm:[1,0,3,2] row_mask:0xf bank_mask:0xf
	v_add_u32_e32 v229, v194, v117
	v_perm_b32 v200, v200, v0, v195
	ds_write_b32 v229, v200
	s_nop 1
	v_mov_b32_dpp v228, v18 quad_perm:[1,0,3,2] row_mask:0xf bank_mask:0xf
	v_perm_b32 v228, v228, v18, v195
	ds_write_b32 v229, v228 offset:288
	v_cvt_pk_bf16_f32 v0, v14, v15
	v_cvt_pk_bf16_f32 v18, v16, v17
	s_nop 1
	v_mov_b32_dpp v200, v0 quad_perm:[1,0,3,2] row_mask:0xf bank_mask:0xf
	v_perm_b32 v200, v200, v0, v195
	ds_write_b32 v229, v200 offset:32
	s_nop 1
	v_mov_b32_dpp v228, v18 quad_perm:[1,0,3,2] row_mask:0xf bank_mask:0xf
	v_perm_b32 v228, v228, v18, v195
	ds_write_b32 v229, v228 offset:320
	v_add_f32_e32 v33, v33, v41
	v_mul_f32_e32 v33, 0xbfb8aa3b, v33
	v_add_f32_e32 v32, v32, v40
	v_exp_f32_e32 v33, v33
	v_mul_f32_e32 v32, 0xbfb8aa3b, v32
	v_exp_f32_e32 v32, v32
	v_add_f32_e32 v31, v31, v39
	v_add_f32_e32 v26, v26, v34
	v_add_f32_e32 v34, v146, v147
	v_mul_f32_e32 v31, 0xbfb8aa3b, v31
	v_add_f32_e32 v33, 1.0, v33
	v_max_f32_e32 v34, 0x179abe15, v34
	v_exp_f32_e32 v31, v31
	v_rcp_f32_e32 v33, v33
	v_sub_f32_e32 v39, v65, v57
	v_rsq_f32_e32 v34, v34
	v_add_f32_e32 v32, 1.0, v32
	v_mul_f32_e32 v39, 0x3fb8aa3b, v39
	v_add_f32_e32 v30, v30, v38
	v_rcp_f32_e32 v32, v32
; template <bool PA> ...
;     ...
; #pragma unroll
;                 for (int e = 0; e < 8; ++e) { av[e] = sigmoidf_(aa[e]); lw[e] = -0.6065306597f * sigmoidf_(z[e]); kd[e] = kv[e] * (1.0f + (av[e] - 1.0f) * cst[192 + c8 + e]); kk[e] *= inv; bsum += rv[e] * kd[e] * cst[256 + c8 + e]; }
;                 bsum += __shfl_xor(bsum, 1); bsum += __shfl_xor(bsum, 2); bsum += __shfl_xor(bsum, 4);
;                 if (!PA && part == 0) beta[((size_t)d * SLAB + row) * 16 + head] = bsum;
;                 *(f32x4_t*)(cumb + j * 64 + c8) = (f32x4_t){lw[0], lw[1], lw[2], lw[3]}; *(f32x4_t*)(cumb + j * 64 + c8 + 4) = (f32x4_t){lw[4], lw[5], lw[6], lw[7]};
;             }
;             __syncthreads();
;             { const int c = tid & 63, sg = tid >> 6; float run = 0.f;
; #pragma unroll
;               for (int i = 0; i < 8; ++i) { run += cumb[(8 * sg + i) * 64 + c]; cumb[(8 * sg + i) * 64 + c] = run; }
;               segtot[sg * 64 + c] = run; }
;             __syncthreads();
;             { const int c = tid & 63, sg = tid >> 6; float off = 0.f;
; #pragma unroll
;               for (int s = 0; s < 7; ++s) off += (s < sg) ? segtot[s * 64 + c] : 0.f;
; #pragma unroll
;               for (int i = 0; i < 8; ++i) cumb[(8 * sg + i) * 64 + c] += off; }
;             __syncthreads();
;             {
;                 const f32x4_t c0 = *(const f32x4_t*)(cumb + j * 64 + c8), c1 = *(const f32x4_t*)(cumb + j * 64 + c8 + 4);
;                 float ah[8], bh[8], kh[8], rh[8];
; #pragma unroll
;                 for (int e = 0; e < 8; ++e) { const float cu = e < 4 ? c0[e & 3] : c1[e & 3]; const float Wt = __expf(cu), iW = __expf(-cu), Wm1 = __expf(cu - lw[e]);
;                     ah[e] = kk[e] * Wm1; bh[e] = -(kk[e] * av[e]) * iW; kh[e] = kd[e] * iW; rh[e] = rv[e] * Wt;
;                     if (j == 63) wc[c8 + e] = Wt; }
;                 u32x4_t w;
;                 w.x = pk2(ah[0], ah[1]); w.y = pk2(ah[2], ah[3]); w.z = pk2(ah[4], ah[5]); w.w = pk2(ah[6], ah[7]); *(u32x4_t*)(MAT(0) + j * 72 + c8) = w;
;                 u32x4_t wb, wk;
;                 wb.x = pk2(bh[0], bh[1]); wb.y = pk2(bh[2], bh[3]); wb.z = pk2(bh[4], bh[5]); wb.w = pk2(bh[6], bh[7]); *(u32x4_t*)(MAT(1) + j * 72 + c8) = wb;
;                 wk.x = pk2(kh[0], kh[1]); wk.y = pk2(kh[2], kh[3]); wk.z = pk2(kh[4], kh[5]); wk.w = pk2(kh[6], kh[7]); *(u32x4_t*)(MAT(2) + j * 72 + c8) = wk;
	v_mul_f32_e32 v38, 0xbfb8aa3b, v65
	v_exp_f32_e32 v39, v39
	v_exp_f32_e32 v38, v38
	v_add_f32_e32 v28, v28, v36
	v_mul_f32_e32 v30, 0xbfb8aa3b, v30
	v_add_f32_e32 v31, 1.0, v31
	v_add_f32_e32 v36, -1.0, v33
	v_mul_f32_e32 v40, 0xbfb8aa3b, v64
	v_add_f32_e32 v29, v29, v37
	v_exp_f32_e32 v30, v30
	v_rcp_f32_e32 v31, v31
	v_fma_f32 v36, v36, v53, 1.0
	v_mul_f32_e32 v37, v176, v34
	v_exp_f32_e32 v40, v40
	v_mul_f32_e32 v36, v36, v175
	v_mul_f32_e32 v39, v37, v39
	v_mul_f32_e64 v33, v37, -v33
	v_add_f32_e32 v37, -1.0, v32
	v_mul_f32_e32 v29, 0xbfb8aa3b, v29
	v_mul_f32_e32 v33, v33, v38
	v_mul_f32_e32 v36, v36, v38
	v_fma_f32 v37, v37, v52, 1.0
	v_mul_f32_e32 v38, v174, v34
	v_sub_f32_e32 v41, v64, v56
	v_mul_f32_e32 v52, 0xbfb8aa3b, v63
	v_exp_f32_e32 v29, v29
	v_mul_f32_e32 v37, v37, v173
	v_mul_f32_e32 v41, 0x3fb8aa3b, v41
	v_mul_f32_e64 v32, v38, -v32
	v_exp_f32_e32 v52, v52
	v_sub_f32_e32 v53, v63, v55
	v_add_f32_e32 v30, 1.0, v30
	v_exp_f32_e32 v41, v41
	v_mul_f32_e32 v32, v32, v40
	v_mul_f32_e32 v37, v37, v40
	v_add_f32_e32 v40, -1.0, v31
	v_mul_f32_e32 v53, 0x3fb8aa3b, v53
	v_mul_f32_e32 v28, 0xbfb8aa3b, v28
	v_rcp_f32_e32 v30, v30
	v_fma_f32 v40, v40, v51, 1.0
	v_mul_f32_e32 v51, v172, v34
	v_exp_f32_e32 v53, v53
	v_exp_f32_e32 v28, v28
	v_mul_f32_e32 v40, v40, v171
	v_mul_f32_e64 v31, v51, -v31
	v_sub_f32_e32 v54, v62, v54
	v_add_f32_e32 v27, v27, v35
	v_add_f32_e32 v29, 1.0, v29
	v_and_b32_e32 v35, 0xffff0000, v25
	v_lshlrev_b32_e32 v25, 16, v25
	v_mul_f32_e32 v31, v31, v52
	v_mul_f32_e32 v40, v40, v52
	v_mul_f32_e32 v52, 0xbfb8aa3b, v62
	v_mul_f32_e32 v54, 0x3fb8aa3b, v54
	v_rcp_f32_e32 v29, v29
	v_mul_f32_e32 v41, v38, v41
	v_mul_f32_e32 v38, v183, v25
	v_and_b32_e32 v25, 0xffff0000, v24
	v_exp_f32_e32 v52, v52
	v_exp_f32_e32 v54, v54
	v_mul_f32_e32 v53, v51, v53
	v_mul_f32_e32 v51, v182, v25
	v_add_f32_e32 v25, -1.0, v30
	v_sub_f32_e32 v49, v61, v49
	v_add_f32_e32 v28, 1.0, v28
	v_fma_f32 v25, v25, v50, 1.0
	v_mul_f32_e32 v55, 0xbfb8aa3b, v61
	v_mul_f32_e32 v49, 0x3fb8aa3b, v49
	v_mul_f32_e32 v27, 0xbfb8aa3b, v27
	v_rcp_f32_e32 v28, v28
	v_mul_f32_e32 v25, v25, v169
	v_mul_f32_e32 v50, v170, v34
	v_exp_f32_e32 v55, v55
	v_exp_f32_e32 v49, v49
	v_exp_f32_e32 v27, v27
	v_mul_f32_e32 v54, v50, v54
	v_mul_f32_e64 v30, v50, -v30
	v_mul_f32_e32 v50, v25, v52
	v_add_f32_e32 v25, -1.0, v29
	v_lshlrev_b32_e32 v24, 16, v24
	v_fma_f32 v25, v25, v45, 1.0
	v_mul_f32_e32 v45, v168, v34
	v_mul_f32_e32 v30, v30, v52
	v_mul_f32_e32 v52, v181, v24
	v_and_b32_e32 v24, 0xffff0000, v23
	v_mul_f32_e32 v25, v25, v167
	v_mul_f32_e64 v29, v45, -v29
	v_sub_f32_e32 v48, v60, v48
	v_mul_f32_e32 v49, v45, v49
	v_mul_f32_e32 v29, v29, v55
	v_mul_f32_e32 v45, v25, v55
	v_mul_f32_e32 v55, v180, v24
	v_add_f32_e32 v24, -1.0, v28
	v_mul_f32_e32 v48, 0x3fb8aa3b, v48
	v_add_f32_e32 v27, 1.0, v27
	v_fma_f32 v24, v24, v44, 1.0
	v_mul_f32_e32 v44, 0xbfb8aa3b, v60
	v_exp_f32_e32 v48, v48
	v_rcp_f32_e32 v27, v27
	v_exp_f32_e32 v44, v44
	v_mul_f32_e32 v25, v166, v34
	v_mul_f32_e32 v24, v24, v165
	v_mul_f32_e32 v48, v25, v48
	v_mul_f32_e64 v25, v25, -v28
	v_sub_f32_e32 v47, v59, v47
	v_mul_f32_e32 v26, 0xbfb8aa3b, v26
	v_mul_f32_e32 v28, v25, v44
	v_mul_f32_e32 v44, v24, v44
	v_add_f32_e32 v24, -1.0, v27
	v_mul_f32_e32 v47, 0x3fb8aa3b, v47
	v_exp_f32_e32 v26, v26
	v_fma_f32 v24, v24, v43, 1.0
	v_mul_f32_e32 v43, 0xbfb8aa3b, v59
	v_exp_f32_e32 v47, v47
	v_exp_f32_e32 v43, v43
	v_mul_f32_e32 v25, v164, v34
	v_add_f32_e32 v26, 1.0, v26
	v_mul_f32_e32 v24, v24, v163
	v_mul_f32_e32 v47, v25, v47
	v_mul_f32_e64 v25, v25, -v27
	v_rcp_f32_e32 v26, v26
	v_mul_f32_e32 v27, v25, v43
	v_mul_f32_e32 v43, v24, v43
	v_mul_f32_e32 v24, v162, v34
	v_sub_f32_e32 v34, v58, v46
	v_mul_f32_e32 v34, 0x3fb8aa3b, v34
	v_lshlrev_b32_e32 v23, 16, v23
	v_mul_f32_e32 v25, 0xbfb8aa3b, v58
	v_exp_f32_e32 v34, v34
	v_mul_f32_e32 v56, v179, v23
	v_and_b32_e32 v23, 0xffff0000, v22
	v_exp_f32_e32 v25, v25
	v_mul_f32_e32 v57, v178, v23
	v_add_f32_e32 v23, -1.0, v26
	v_fma_f32 v23, v23, v42, 1.0
	v_lshlrev_b32_e32 v22, 16, v22
	v_mul_f32_e32 v23, v23, v161
	v_mul_f32_e32 v34, v24, v34
	v_mul_f32_e64 v24, v24, -v26
	v_mul_f32_e32 v35, v184, v35
	v_mul_f32_e32 v26, v24, v25
	v_mul_f32_e32 v42, v23, v25
	v_mul_f32_e32 v46, v177, v22
	v_cvt_pk_bf16_f32 v22, v34, v47
	v_cvt_pk_bf16_f32 v23, v48, v49
	v_cvt_pk_bf16_f32 v24, v54, v53
	v_cvt_pk_bf16_f32 v25, v41, v39
	ds_write_b128 v68, v[22:25]
	v_cvt_pk_bf16_f32 v22, v26, v27
	v_cvt_pk_bf16_f32 v23, v28, v29
	v_cvt_pk_bf16_f32 v24, v30, v31
	v_cvt_pk_bf16_f32 v25, v32, v33
	v_cvt_pk_bf16_f32 v26, v42, v43
	v_cvt_pk_bf16_f32 v27, v44, v45
	v_cvt_pk_bf16_f32 v28, v50, v40
	v_cvt_pk_bf16_f32 v29, v37, v36
	v_cvt_pk_bf16_f32 v30, v46, v57
	v_cvt_pk_bf16_f32 v31, v56, v55
	v_cvt_pk_bf16_f32 v32, v52, v51
	v_cvt_pk_bf16_f32 v33, v38, v35
	ds_write_b128 v68, v[22:25] offset:9216
	ds_write_b128 v68, v[26:29] offset:18432
	ds_write_b128 v68, v[30:33] offset:27648
	ds_write_b16 v154, v22 offset:36864
	ds_write_b16_d16_hi v154, v22 offset:37008
	ds_write_b16 v154, v26 offset:46080
	ds_write_b16_d16_hi v154, v26 offset:46224
	s_nop 0
	ds_write_b16 v154, v23 offset:37152
	ds_write_b16_d16_hi v154, v23 offset:37296
	ds_write_b16 v154, v27 offset:46368
	ds_write_b16_d16_hi v154, v27 offset:46512
	ds_write_b16 v185, v24 offset:37440
	ds_write_b16_d16_hi v185, v24 offset:37584
	ds_write_b16 v185, v28 offset:46656
	ds_write_b16_d16_hi v185, v28 offset:46800
	ds_write_b16 v185, v25 offset:37728
	ds_write_b16_d16_hi v185, v25 offset:37872
	ds_write_b16 v185, v29 offset:46944
	ds_write_b16_d16_hi v185, v29 offset:47088
	s_waitcnt lgkmcnt(0)
	s_barrier
; template <bool PA> ...
;     ...
;             f32x4_t Pacc[2], Tacc[2], Xacc[2], Yacc[2], tmp[2];
;             const f32x4_t z4 = (f32x4_t){0.f, 0.f, 0.f, 0.f};
;             Tacc[0] = z4; Tacc[1] = z4;
;             if (!haveT) {
;             Pacc[0] = z4; Pacc[1] = z4; mm2(Pacc, MAT(0), MAT(1), mt, ntb, r16, kq);
; #pragma unroll
;             for (int i = 0; i < 2; ++i)
; #pragma unroll
;                 for (int e = 0; e < 4; ++e) { const int t = 16 * mt + 4 * kq + e, s = 16 * (ntb + i) + r16; Pacc[i][e] = (s < t) ? Pacc[i][e] : 0.f; Tacc[i][e] = Pacc[i][e] + ((s == t) ? 1.f : 0.f); }
;             st_rm(MAT(8), Pacc, mt, ntb, r16, kq); st_tr(MAT(9), Pacc, mt, ntb, r16, kq);
;             }
;             tmp[0] = z4; tmp[1] = z4; mm2(tmp, MAT(0), MAT(2), mt, ntb, r16, kq);
; #pragma unroll
;             for (int i = 0; i < 2; ++i)
; #pragma unroll
;                 for (int e = 0; e < 4; ++e) { const int t = 16 * mt + 4 * kq + e, s = 16 * (ntb + i) + r16; tmp[i][e] = (s < t) ? tmp[i][e] : 0.f; }
;             st_rm(MAT(10), tmp, mt, ntb, r16, kq);
;             f32x4_t X2acc[2]; X2acc[0] = z4; X2acc[1] = z4;
;             if (PA) mm2(X2acc, MAT(0), MAT(12), mt, ntb, r16, kq);
;             if (!PA) {
;             tmp[0] = z4; tmp[1] = z4; mm2(tmp, MAT(3), MAT(1), mt, ntb, r16, kq);
; #pragma unroll
;             for (int i = 0; i < 2; ++i)
; #pragma unroll
;                 for (int e = 0; e < 4; ++e) { const int t = 16 * mt + 4 * kq + e, s = 16 * (ntb + i) + r16; tmp[i][e] = (s <= t) ? tmp[i][e] : 0.f; }
;             st_rm(MAT(11), tmp, mt, ntb, r16, kq);
;             tmp[0] = z4; tmp[1] = z4; mm2(tmp, MAT(3), MAT(2), mt, ntb, r16, kq);
; #pragma unroll
;             for (int i = 0; i < 2; ++i)
; #pragma unroll
;                 for (int e = 0; e < 4; ++e) { const int t = 16 * mt + 4 * kq + e, s = 16 * (ntb + i) + r16; tmp[i][e] = (s <= t) ? tmp[i][e] : 0.f; }
;             st_rm(MAT(12), tmp, mt, ntb, r16, kq);
;             }
;             Xacc[0] = z4; Xacc[1] = z4; mm2(Xacc, MAT(0), MAT(7), mt, ntb, r16, kq);
;             Yacc[0] = z4; Yacc[1] = z4; if (!PA) mm2(Yacc, MAT(3), MAT(7), mt, ntb, r16, kq);
;             __syncthreads();
;             if (!haveT) {
;             tmp[0] = z4; tmp[1] = z4; mm2(tmp, MAT(8), MAT(9), mt, ntb, r16, kq);
	ds_read_b128 v[186:189], v69
	ds_read_b128 v[190:193], v118 offset:9216
	ds_read_b128 v[204:207], v118 offset:11520
	ds_read_b128 v[208:211], v69 offset:64
	ds_read_b128 v[212:215], v118 offset:9280
	ds_read_b128 v[216:219], v118 offset:11584
	ds_read_b128 v[220:223], v69
	ds_read_b128 v[224:227], v118 offset:18432
	s_nop 0
	s_nop 0
	s_nop 0
	s_waitcnt lgkmcnt(6)
	v_mfma_f32_16x16x32_bf16 v[22:25], v[186:189], v[190:193], 0
	ds_read_b128 v[190:193], v118 offset:20736
	s_waitcnt lgkmcnt(6)
	v_mfma_f32_16x16x32_bf16 v[18:21], v[186:189], v[204:207], 0
	ds_read_b128 v[186:189], v69 offset:64
	ds_read_b128 v[204:207], v118 offset:18496
	s_nop 0
	s_nop 0
	s_waitcnt lgkmcnt(6)
	v_mfma_f32_16x16x32_bf16 v[22:25], v[208:211], v[212:215], v[22:25]
	ds_read_b128 v[212:215], v118 offset:20800
	s_nop 0
	s_waitcnt lgkmcnt(6)
	v_mfma_f32_16x16x32_bf16 v[18:21], v[208:211], v[216:219], v[18:21]
	s_nop 4
	v_cndmask_b32_e64 v0, 0, v22, s[58:59]
	v_cndmask_b32_e64 v22, v23, 0, s[60:61]
	v_cndmask_b32_e64 v23, 0, v24, s[62:63]
	v_cndmask_b32_e64 v24, 0, v25, s[64:65]
	v_cndmask_b32_e64 v25, 0, v18, s[66:67]
	v_cndmask_b32_e64 v26, v19, 0, s[68:69]
	v_cndmask_b32_e64 v27, 0, v20, s[70:71]
	v_cndmask_b32_e64 v21, 0, v21, s[72:73]
	v_add_f32_e32 v65, v143, v21
	v_cvt_pk_bf16_f32 v18, v0, v22
	v_cvt_pk_bf16_f32 v20, v25, v26
	v_cvt_pk_bf16_f32 v21, v27, v21
	v_cvt_pk_bf16_f32 v19, v23, v24
	s_nop 1
	v_mov_b32_dpp v200, v18 quad_perm:[1,0,3,2] row_mask:0xf bank_mask:0xf
	v_add_u32_e32 v229, v194, v119
	v_perm_b32 v200, v200, v18, v195
	ds_write_b32 v229, v200
	s_nop 1
	v_mov_b32_dpp v228, v19 quad_perm:[1,0,3,2] row_mask:0xf bank_mask:0xf
	v_perm_b32 v228, v228, v19, v195
	ds_write_b32 v229, v228 offset:288
	s_nop 1
	v_mov_b32_dpp v200, v20 quad_perm:[1,0,3,2] row_mask:0xf bank_mask:0xf
	v_perm_b32 v200, v200, v20, v195
	ds_write_b32 v229, v200 offset:32
	s_nop 1
	v_mov_b32_dpp v228, v21 quad_perm:[1,0,3,2] row_mask:0xf bank_mask:0xf
	v_perm_b32 v228, v228, v21, v195
	ds_write_b32 v229, v228 offset:320
	ds_write_b64 v120, v[18:19]
	ds_write_b64 v120, v[20:21] offset:2304
	v_add_f32_e32 v59, v137, v22
	v_add_f32_e32 v60, v138, v23
	v_add_f32_e32 v61, v139, v24
	v_add_f32_e32 v62, v140, v25
	v_add_f32_e32 v63, v141, v26
	v_add_f32_e32 v64, v142, v27
	s_nop 0
	s_nop 0
	s_nop 0
	s_waitcnt lgkmcnt(0)
	v_mfma_f32_16x16x32_bf16 v[22:25], v[220:223], v[224:227], 0
	v_add_f32_e32 v58, v136, v0
	s_waitcnt lgkmcnt(0)
	v_mfma_f32_16x16x32_bf16 v[18:21], v[220:223], v[190:193], 0
	s_nop 0
	s_nop 0
	s_waitcnt lgkmcnt(0)
	v_mfma_f32_16x16x32_bf16 v[22:25], v[186:189], v[204:207], v[22:25]
	s_nop 0
	s_waitcnt lgkmcnt(0)
	v_mfma_f32_16x16x32_bf16 v[18:21], v[186:189], v[212:215], v[18:21]
	s_nop 4
	v_cndmask_b32_e64 v0, 0, v22, s[58:59]
	v_cndmask_b32_e64 v22, v23, 0, s[60:61]
	v_cndmask_b32_e64 v23, 0, v24, s[62:63]
	v_cndmask_b32_e64 v24, 0, v25, s[64:65]
	v_cndmask_b32_e64 v18, 0, v18, s[66:67]
	v_cndmask_b32_e64 v19, v19, 0, s[68:69]
	v_cvt_pk_bf16_f32 v0, v0, v22
	v_cndmask_b32_e64 v20, 0, v20, s[70:71]
	v_cndmask_b32_e64 v21, 0, v21, s[72:73]
	v_cvt_pk_bf16_f32 v22, v23, v24
	s_nop 1
	v_mov_b32_dpp v200, v0 quad_perm:[1,0,3,2] row_mask:0xf bank_mask:0xf
	v_add_u32_e32 v229, v194, v121
	v_perm_b32 v200, v200, v0, v195
	ds_write_b32 v229, v200
	s_nop 1
	v_mov_b32_dpp v228, v22 quad_perm:[1,0,3,2] row_mask:0xf bank_mask:0xf
	v_perm_b32 v228, v228, v22, v195
	ds_write_b32 v229, v228 offset:288
	v_cvt_pk_bf16_f32 v0, v18, v19
	v_cvt_pk_bf16_f32 v18, v20, v21
	s_nop 1
	v_mov_b32_dpp v200, v0 quad_perm:[1,0,3,2] row_mask:0xf bank_mask:0xf
	v_perm_b32 v200, v200, v0, v195
	ds_write_b32 v229, v200 offset:32
	s_nop 1
	v_mov_b32_dpp v228, v18 quad_perm:[1,0,3,2] row_mask:0xf bank_mask:0xf
	v_perm_b32 v228, v228, v18, v195
	ds_write_b32 v229, v228 offset:320
	ds_read_b128 v[22:25], v69
	ds_read_b128 v[42:45], v122
	ds_read_b128 v[46:49], v122 offset:2304
	ds_read_b128 v[18:21], v69 offset:64
	ds_read_b128 v[54:57], v122 offset:64
	ds_read_b128 v[50:53], v122 offset:2368
	ds_read_b128 v[38:41], v118 offset:64512
	ds_read_b128 v[34:37], v123
	ds_read_b128 v[30:33], v118 offset:64576
	ds_read_b128 v[26:29], v124
	s_waitcnt lgkmcnt(0)
	s_barrier
	ds_read_b128 v[186:189], v125
	ds_read_b128 v[190:193], v126
	ds_read_b128 v[204:207], v126 offset:2304
	ds_read_b128 v[208:211], v125 offset:64
	ds_read_b128 v[212:215], v126 offset:64
	ds_read_b128 v[216:219], v126 offset:2368
	s_nop 0
	s_nop 0
	s_nop 0
	s_waitcnt lgkmcnt(4)
	v_mfma_f32_16x16x32_bf16 v[166:169], v[186:189], v[190:193], 0
	v_cvt_pk_bf16_f32 v0, v58, v59
	s_waitcnt lgkmcnt(3)
	v_mfma_f32_16x16x32_bf16 v[162:165], v[186:189], v[204:207], 0
	s_nop 0
	s_nop 0
	s_waitcnt lgkmcnt(1)
	v_mfma_f32_16x16x32_bf16 v[166:169], v[208:211], v[212:215], v[166:169]
	s_nop 0
	s_waitcnt lgkmcnt(0)
	v_mfma_f32_16x16x32_bf16 v[162:165], v[208:211], v[216:219], v[162:165]
	s_nop 4
	v_cvt_pk_bf16_f32 v146, v166, v167
	v_cvt_pk_bf16_f32 v147, v168, v169
	s_nop 1
	v_mov_b32_dpp v200, v146 quad_perm:[1,0,3,2] row_mask:0xf bank_mask:0xf
	v_add_u32_e32 v229, v194, v116
	v_perm_b32 v200, v200, v146, v195
	ds_write_b32 v229, v200
	s_nop 1
	v_mov_b32_dpp v228, v147 quad_perm:[1,0,3,2] row_mask:0xf bank_mask:0xf
	v_perm_b32 v228, v228, v147, v195
	ds_write_b32 v229, v228 offset:288
	v_cvt_pk_bf16_f32 v162, v162, v163
	v_cvt_pk_bf16_f32 v163, v164, v165
	s_nop 1
	v_mov_b32_dpp v200, v162 quad_perm:[1,0,3,2] row_mask:0xf bank_mask:0xf
	v_perm_b32 v200, v200, v162, v195
	ds_write_b32 v229, v200 offset:32
	s_nop 1
	v_mov_b32_dpp v228, v163 quad_perm:[1,0,3,2] row_mask:0xf bank_mask:0xf
	v_perm_b32 v228, v228, v163, v195
	ds_write_b32 v229, v228 offset:320
	ds_write_b64 v127, v[146:147] offset:9216
	ds_write_b64 v127, v[162:163] offset:11520
	v_cvt_pk_bf16_f32 v146, v60, v61
	s_nop 1
	v_mov_b32_dpp v200, v0 quad_perm:[1,0,3,2] row_mask:0xf bank_mask:0xf
	v_perm_b32 v200, v200, v0, v195
	ds_write_b32 v229, v200 offset:18432
	s_nop 1
	v_mov_b32_dpp v228, v146 quad_perm:[1,0,3,2] row_mask:0xf bank_mask:0xf
	v_perm_b32 v228, v228, v146, v195
	ds_write_b32 v229, v228 offset:18720
	v_cvt_pk_bf16_f32 v0, v62, v63
	v_cvt_pk_bf16_f32 v146, v64, v65
	s_nop 1
	v_mov_b32_dpp v200, v0 quad_perm:[1,0,3,2] row_mask:0xf bank_mask:0xf
	v_perm_b32 v200, v200, v0, v195
	ds_write_b32 v229, v200 offset:18464
	s_nop 1
	v_mov_b32_dpp v228, v146 quad_perm:[1,0,3,2] row_mask:0xf bank_mask:0xf
	v_perm_b32 v228, v228, v146, v195
	ds_write_b32 v229, v228 offset:18752
	s_waitcnt lgkmcnt(0)
	s_barrier
; template <bool PA> ...
;     ...
; #pragma unroll
;             for (int i = 1; i <= 5; ++i) {
;                 bf16* Pc = (i & 1) ? MAT(0) : MAT(8); bf16* PcT = (i & 1) ? MAT(1) : MAT(9); bf16* Pn = (i & 1) ? MAT(8) : MAT(0); bf16* PnT = (i & 1) ? MAT(9) : MAT(1);
;                 bf16* Tc = (i & 1) ? MAT(2) : MAT(3); bf16* Tn = (i & 1) ? MAT(3) : MAT(2);
;                 mm2(Tacc, Tc, PcT, mt, ntb, r16, kq);
;                 if (i < 5) { tmp[0] = z4; tmp[1] = z4; mm2(tmp, Pc, PcT, mt, ntb, r16, kq); st_rm(Pn, tmp, mt, ntb, r16, kq); st_tr(PnT, tmp, mt, ntb, r16, kq); }
;                 st_rm(Tn, Tacc, mt, ntb, r16, kq);
;                 __syncthreads();
;             }
	ds_read_b128 v[186:189], v69 offset:18432
	ds_read_b128 v[190:193], v118 offset:9216
	ds_read_b128 v[204:207], v118 offset:11520
	ds_read_b128 v[208:211], v69 offset:18496
	ds_read_b128 v[212:215], v118 offset:9280
	ds_read_b128 v[216:219], v118 offset:11584
	ds_read_b128 v[220:223], v69
	ds_read_b128 v[224:227], v69 offset:64
	s_nop 0
	s_nop 0
	s_nop 0
	s_waitcnt lgkmcnt(6)
	v_mfma_f32_16x16x32_bf16 v[58:61], v[186:189], v[190:193], v[58:61]
	s_waitcnt lgkmcnt(5)
	v_mfma_f32_16x16x32_bf16 v[62:65], v[186:189], v[204:207], v[62:65]
	s_nop 0
	s_nop 0
	s_nop 0
	s_waitcnt lgkmcnt(3)
	v_mfma_f32_16x16x32_bf16 v[58:61], v[208:211], v[212:215], v[58:61]
	s_waitcnt lgkmcnt(2)
	v_mfma_f32_16x16x32_bf16 v[62:65], v[208:211], v[216:219], v[62:65]
	s_nop 0
	s_nop 4
	v_cvt_pk_bf16_f32 v0, v58, v59
	s_waitcnt lgkmcnt(1)
	v_mfma_f32_16x16x32_bf16 v[166:169], v[220:223], v[190:193], 0
	v_mfma_f32_16x16x32_bf16 v[162:165], v[220:223], v[204:207], 0
	s_nop 0
	s_waitcnt lgkmcnt(0)
	v_mfma_f32_16x16x32_bf16 v[166:169], v[224:227], v[212:215], v[166:169]
	s_nop 7
	v_cvt_pk_bf16_f32 v146, v166, v167
	v_mfma_f32_16x16x32_bf16 v[162:165], v[224:227], v[216:219], v[162:165]
	v_cvt_pk_bf16_f32 v147, v168, v169
	s_nop 1
	v_mov_b32_dpp v200, v146 quad_perm:[1,0,3,2] row_mask:0xf bank_mask:0xf
	v_add_u32_e32 v229, v194, v155
	v_perm_b32 v200, v200, v146, v195
	ds_write_b32 v229, v200
	s_nop 1
	v_mov_b32_dpp v228, v147 quad_perm:[1,0,3,2] row_mask:0xf bank_mask:0xf
	v_perm_b32 v228, v228, v147, v195
	ds_write_b32 v229, v228 offset:288
	s_nop 2
	v_cvt_pk_bf16_f32 v162, v162, v163
	v_cvt_pk_bf16_f32 v163, v164, v165
	s_nop 1
	v_mov_b32_dpp v200, v162 quad_perm:[1,0,3,2] row_mask:0xf bank_mask:0xf
	v_perm_b32 v200, v200, v162, v195
	ds_write_b32 v229, v200 offset:32
	s_nop 1
	v_mov_b32_dpp v228, v163 quad_perm:[1,0,3,2] row_mask:0xf bank_mask:0xf
	v_perm_b32 v228, v228, v163, v195
	ds_write_b32 v229, v228 offset:320
	ds_write_b64 v120, v[146:147]
	ds_write_b64 v120, v[162:163] offset:2304
	v_cvt_pk_bf16_f32 v146, v60, v61
	s_nop 1
	v_mov_b32_dpp v200, v0 quad_perm:[1,0,3,2] row_mask:0xf bank_mask:0xf
	v_add_u32_e32 v229, v194, v156
	v_perm_b32 v200, v200, v0, v195
	ds_write_b32 v229, v200 offset:27648
	s_nop 1
	v_mov_b32_dpp v228, v146 quad_perm:[1,0,3,2] row_mask:0xf bank_mask:0xf
	v_perm_b32 v228, v228, v146, v195
	ds_write_b32 v229, v228 offset:27936
	v_cvt_pk_bf16_f32 v0, v62, v63
	v_cvt_pk_bf16_f32 v146, v64, v65
	s_nop 1
	v_mov_b32_dpp v200, v0 quad_perm:[1,0,3,2] row_mask:0xf bank_mask:0xf
	v_perm_b32 v200, v200, v0, v195
	ds_write_b32 v229, v200 offset:27680
	s_nop 1
	v_mov_b32_dpp v228, v146 quad_perm:[1,0,3,2] row_mask:0xf bank_mask:0xf
	v_perm_b32 v228, v228, v146, v195
	ds_write_b32 v229, v228 offset:27968
	s_waitcnt lgkmcnt(0)
	s_barrier
	ds_read_b128 v[186:189], v69 offset:27648
	ds_read_b128 v[190:193], v126
	ds_read_b128 v[204:207], v126 offset:2304
	ds_read_b128 v[208:211], v69 offset:27712
	ds_read_b128 v[212:215], v126 offset:64
	ds_read_b128 v[216:219], v126 offset:2368
	ds_read_b128 v[220:223], v125
	ds_read_b128 v[224:227], v125 offset:64
	s_nop 0
	s_nop 0
	s_nop 0
	s_waitcnt lgkmcnt(6)
	v_mfma_f32_16x16x32_bf16 v[58:61], v[186:189], v[190:193], v[58:61]
	s_waitcnt lgkmcnt(5)
	v_mfma_f32_16x16x32_bf16 v[62:65], v[186:189], v[204:207], v[62:65]
	s_nop 0
	s_nop 0
	s_nop 0
	s_waitcnt lgkmcnt(3)
	v_mfma_f32_16x16x32_bf16 v[58:61], v[208:211], v[212:215], v[58:61]
	s_waitcnt lgkmcnt(2)
	v_mfma_f32_16x16x32_bf16 v[62:65], v[208:211], v[216:219], v[62:65]
	s_nop 0
	s_nop 4
	v_cvt_pk_bf16_f32 v0, v58, v59
	s_waitcnt lgkmcnt(1)
	v_mfma_f32_16x16x32_bf16 v[166:169], v[220:223], v[190:193], 0
	v_mfma_f32_16x16x32_bf16 v[162:165], v[220:223], v[204:207], 0
	s_nop 0
	s_waitcnt lgkmcnt(0)
	v_mfma_f32_16x16x32_bf16 v[166:169], v[224:227], v[212:215], v[166:169]
	s_nop 7
	v_cvt_pk_bf16_f32 v146, v166, v167
	v_mfma_f32_16x16x32_bf16 v[162:165], v[224:227], v[216:219], v[162:165]
	v_cvt_pk_bf16_f32 v147, v168, v169
	s_nop 1
	v_mov_b32_dpp v200, v146 quad_perm:[1,0,3,2] row_mask:0xf bank_mask:0xf
	v_perm_b32 v200, v200, v146, v195
	ds_write_b32 v229, v200
	s_nop 1
	v_mov_b32_dpp v228, v147 quad_perm:[1,0,3,2] row_mask:0xf bank_mask:0xf
	v_perm_b32 v228, v228, v147, v195
	ds_write_b32 v229, v228 offset:288
	s_nop 2
	v_cvt_pk_bf16_f32 v162, v162, v163
	v_cvt_pk_bf16_f32 v163, v164, v165
	s_nop 1
	v_mov_b32_dpp v200, v162 quad_perm:[1,0,3,2] row_mask:0xf bank_mask:0xf
	v_perm_b32 v200, v200, v162, v195
	ds_write_b32 v229, v200 offset:32
	s_nop 1
	v_mov_b32_dpp v228, v163 quad_perm:[1,0,3,2] row_mask:0xf bank_mask:0xf
	v_perm_b32 v228, v228, v163, v195
	ds_write_b32 v229, v228 offset:320
	ds_write_b64 v127, v[146:147] offset:9216
	ds_write_b64 v127, v[162:163] offset:11520
	v_cvt_pk_bf16_f32 v146, v60, v61
	s_nop 1
	v_mov_b32_dpp v200, v0 quad_perm:[1,0,3,2] row_mask:0xf bank_mask:0xf
	v_perm_b32 v200, v200, v0, v195
	ds_write_b32 v229, v200 offset:18432
	s_nop 1
	v_mov_b32_dpp v228, v146 quad_perm:[1,0,3,2] row_mask:0xf bank_mask:0xf
	v_perm_b32 v228, v228, v146, v195
	ds_write_b32 v229, v228 offset:18720
	v_cvt_pk_bf16_f32 v0, v62, v63
	v_cvt_pk_bf16_f32 v146, v64, v65
	s_nop 1
	v_mov_b32_dpp v200, v0 quad_perm:[1,0,3,2] row_mask:0xf bank_mask:0xf
	v_perm_b32 v200, v200, v0, v195
	ds_write_b32 v229, v200 offset:18464
	s_nop 1
	v_mov_b32_dpp v228, v146 quad_perm:[1,0,3,2] row_mask:0xf bank_mask:0xf
	v_perm_b32 v228, v228, v146, v195
	ds_write_b32 v229, v228 offset:18752
	s_waitcnt lgkmcnt(0)
	s_barrier
; template <bool PA> ...
;     ...
;             for (int i = 1; i <= 5; ++i) {
;                 bf16* Pc = (i & 1) ? MAT(0) : MAT(8); bf16* PcT = (i & 1) ? MAT(1) : MAT(9); bf16* Pn = (i & 1) ? MAT(8) : MAT(0); bf16* PnT = (i & 1) ? MAT(9) : MAT(1);
;                 bf16* Tc = (i & 1) ? MAT(2) : MAT(3); bf16* Tn = (i & 1) ? MAT(3) : MAT(2);
;                 mm2(Tacc, Tc, PcT, mt, ntb, r16, kq);
;                 if (i < 5) { tmp[0] = z4; tmp[1] = z4; mm2(tmp, Pc, PcT, mt, ntb, r16, kq); st_rm(Pn, tmp, mt, ntb, r16, kq); st_tr(PnT, tmp, mt, ntb, r16, kq); }
;                 st_rm(Tn, Tacc, mt, ntb, r16, kq);
;                 __syncthreads();
	ds_read_b128 v[186:189], v69 offset:18432
	ds_read_b128 v[190:193], v118 offset:9216
	ds_read_b128 v[204:207], v118 offset:11520
	ds_read_b128 v[208:211], v69 offset:18496
	ds_read_b128 v[212:215], v118 offset:9280
	ds_read_b128 v[216:219], v118 offset:11584
	ds_read_b128 v[220:223], v69
	ds_read_b128 v[224:227], v69 offset:64
	s_nop 0
	s_nop 0
	s_nop 0
	s_waitcnt lgkmcnt(6)
	v_mfma_f32_16x16x32_bf16 v[58:61], v[186:189], v[190:193], v[58:61]
	s_waitcnt lgkmcnt(5)
	v_mfma_f32_16x16x32_bf16 v[62:65], v[186:189], v[204:207], v[62:65]
	s_nop 0
	s_nop 0
	s_nop 0
	s_waitcnt lgkmcnt(3)
	v_mfma_f32_16x16x32_bf16 v[58:61], v[208:211], v[212:215], v[58:61]
	s_waitcnt lgkmcnt(2)
	v_mfma_f32_16x16x32_bf16 v[62:65], v[208:211], v[216:219], v[62:65]
	s_nop 0
	s_nop 4
	v_cvt_pk_bf16_f32 v0, v58, v59
	s_waitcnt lgkmcnt(1)
	v_mfma_f32_16x16x32_bf16 v[166:169], v[220:223], v[190:193], 0
	v_mfma_f32_16x16x32_bf16 v[162:165], v[220:223], v[204:207], 0
	s_nop 0
	s_waitcnt lgkmcnt(0)
	v_mfma_f32_16x16x32_bf16 v[166:169], v[224:227], v[212:215], v[166:169]
	s_nop 7
	v_cvt_pk_bf16_f32 v146, v166, v167
	v_mfma_f32_16x16x32_bf16 v[162:165], v[224:227], v[216:219], v[162:165]
	v_cvt_pk_bf16_f32 v147, v168, v169
	s_nop 1
	v_mov_b32_dpp v200, v146 quad_perm:[1,0,3,2] row_mask:0xf bank_mask:0xf
	v_add_u32_e32 v229, v194, v155
	v_perm_b32 v200, v200, v146, v195
	ds_write_b32 v229, v200
	s_nop 1
	v_mov_b32_dpp v228, v147 quad_perm:[1,0,3,2] row_mask:0xf bank_mask:0xf
	v_perm_b32 v228, v228, v147, v195
	ds_write_b32 v229, v228 offset:288
	s_nop 2
	v_cvt_pk_bf16_f32 v162, v162, v163
	v_cvt_pk_bf16_f32 v163, v164, v165
	s_nop 1
	v_mov_b32_dpp v200, v162 quad_perm:[1,0,3,2] row_mask:0xf bank_mask:0xf
	v_perm_b32 v200, v200, v162, v195
	ds_write_b32 v229, v200 offset:32
	s_nop 1
	v_mov_b32_dpp v228, v163 quad_perm:[1,0,3,2] row_mask:0xf bank_mask:0xf
	v_perm_b32 v228, v228, v163, v195
	ds_write_b32 v229, v228 offset:320
	ds_write_b64 v120, v[146:147]
	ds_write_b64 v120, v[162:163] offset:2304
	v_cvt_pk_bf16_f32 v146, v60, v61
	s_nop 1
	v_mov_b32_dpp v200, v0 quad_perm:[1,0,3,2] row_mask:0xf bank_mask:0xf
	v_add_u32_e32 v229, v194, v156
	v_perm_b32 v200, v200, v0, v195
	ds_write_b32 v229, v200 offset:27648
	s_nop 1
	v_mov_b32_dpp v228, v146 quad_perm:[1,0,3,2] row_mask:0xf bank_mask:0xf
	v_perm_b32 v228, v228, v146, v195
	ds_write_b32 v229, v228 offset:27936
	v_cvt_pk_bf16_f32 v0, v62, v63
	v_cvt_pk_bf16_f32 v146, v64, v65
	s_nop 1
	v_mov_b32_dpp v200, v0 quad_perm:[1,0,3,2] row_mask:0xf bank_mask:0xf
	v_perm_b32 v200, v200, v0, v195
	ds_write_b32 v229, v200 offset:27680
	s_nop 1
	v_mov_b32_dpp v228, v146 quad_perm:[1,0,3,2] row_mask:0xf bank_mask:0xf
	v_perm_b32 v228, v228, v146, v195
	ds_write_b32 v229, v228 offset:27968
	s_waitcnt lgkmcnt(0)
	s_barrier
; template <bool PA> ...
;     ...
;             Xacc[0] = z4; Xacc[1] = z4; mm2(Xacc, MAT(0), MAT(7), mt, ntb, r16, kq);
;             Yacc[0] = z4; Yacc[1] = z4; if (!PA) mm2(Yacc, MAT(3), MAT(7), mt, ntb, r16, kq);
;             __syncthreads();
;             if (!haveT) {
;             tmp[0] = z4; tmp[1] = z4; mm2(tmp, MAT(8), MAT(9), mt, ntb, r16, kq);
;             st_rm(MAT(0), tmp, mt, ntb, r16, kq); st_tr(MAT(1), tmp, mt, ntb, r16, kq); st_rm(MAT(2), Tacc, mt, ntb, r16, kq);
;             __syncthreads();
; #pragma unroll
;             for (int i = 1; i <= 5; ++i) {
;                 bf16* Pc = (i & 1) ? MAT(0) : MAT(8); bf16* PcT = (i & 1) ? MAT(1) : MAT(9); bf16* Pn = (i & 1) ? MAT(8) : MAT(0); bf16* PnT = (i & 1) ? MAT(9) : MAT(1);
;                 bf16* Tc = (i & 1) ? MAT(2) : MAT(3); bf16* Tn = (i & 1) ? MAT(3) : MAT(2);
;                 mm2(Tacc, Tc, PcT, mt, ntb, r16, kq);
;                 if (i < 5) { tmp[0] = z4; tmp[1] = z4; mm2(tmp, Pc, PcT, mt, ntb, r16, kq); st_rm(Pn, tmp, mt, ntb, r16, kq); st_tr(PnT, tmp, mt, ntb, r16, kq); }
;                 st_rm(Tn, Tacc, mt, ntb, r16, kq);
;                 __syncthreads();
;             }
;             }
;             if (PA && tlow) *(u32x4_t*)(tbuf + ((size_t)strm * NCHA + p) * 2304 + tunit * 8) = *(const u32x4_t*)(MAT(3) + j * 72 + c8);
	ds_read_b128 v[186:189], v69 offset:27648
	ds_read_b128 v[190:193], v126
	ds_read_b128 v[204:207], v126 offset:2304
	ds_read_b128 v[208:211], v69 offset:27712
	ds_read_b128 v[212:215], v126 offset:64
	ds_read_b128 v[216:219], v126 offset:2368
	ds_read_b128 v[220:223], v125
	ds_read_b128 v[224:227], v125 offset:64
	s_nop 0
	s_nop 0
	s_nop 0
	s_waitcnt lgkmcnt(6)
	v_mfma_f32_16x16x32_bf16 v[58:61], v[186:189], v[190:193], v[58:61]
	s_waitcnt lgkmcnt(5)
	v_mfma_f32_16x16x32_bf16 v[62:65], v[186:189], v[204:207], v[62:65]
	s_nop 0
	s_nop 0
	s_nop 0
	s_waitcnt lgkmcnt(3)
	v_mfma_f32_16x16x32_bf16 v[58:61], v[208:211], v[212:215], v[58:61]
	s_waitcnt lgkmcnt(2)
	v_mfma_f32_16x16x32_bf16 v[62:65], v[208:211], v[216:219], v[62:65]
	s_nop 0
	s_nop 4
	v_cvt_pk_bf16_f32 v0, v58, v59
	s_waitcnt lgkmcnt(1)
	v_mfma_f32_16x16x32_bf16 v[166:169], v[220:223], v[190:193], 0
	v_mfma_f32_16x16x32_bf16 v[162:165], v[220:223], v[204:207], 0
	s_nop 0
	s_waitcnt lgkmcnt(0)
	v_mfma_f32_16x16x32_bf16 v[166:169], v[224:227], v[212:215], v[166:169]
	v_mov_b32_e32 v174, v212
	v_mov_b32_e32 v175, v213
	v_mov_b32_e32 v176, v214
	v_mov_b32_e32 v177, v215
	s_nop 7
	v_cvt_pk_bf16_f32 v146, v166, v167
	v_mfma_f32_16x16x32_bf16 v[162:165], v[224:227], v[216:219], v[162:165]
	v_mov_b32_e32 v178, v216
	v_mov_b32_e32 v179, v217
	v_mov_b32_e32 v180, v218
	v_mov_b32_e32 v181, v219
	v_mov_b32_e32 v170, v224
	v_mov_b32_e32 v171, v225
	v_mov_b32_e32 v172, v226
	v_mov_b32_e32 v173, v227
	v_cvt_pk_bf16_f32 v147, v168, v169
	s_nop 1
	v_mov_b32_dpp v200, v146 quad_perm:[1,0,3,2] row_mask:0xf bank_mask:0xf
	v_perm_b32 v200, v200, v146, v195
	ds_write_b32 v229, v200
	s_nop 1
	v_mov_b32_dpp v228, v147 quad_perm:[1,0,3,2] row_mask:0xf bank_mask:0xf
	v_perm_b32 v228, v228, v147, v195
	ds_write_b32 v229, v228 offset:288
	s_nop 2
	v_cvt_pk_bf16_f32 v162, v162, v163
	v_cvt_pk_bf16_f32 v163, v164, v165
	s_nop 1
	v_mov_b32_dpp v200, v162 quad_perm:[1,0,3,2] row_mask:0xf bank_mask:0xf
	v_perm_b32 v200, v200, v162, v195
	ds_write_b32 v229, v200 offset:32
	s_nop 1
	v_mov_b32_dpp v228, v163 quad_perm:[1,0,3,2] row_mask:0xf bank_mask:0xf
	v_perm_b32 v228, v228, v163, v195
	ds_write_b32 v229, v228 offset:320
	ds_write_b64 v127, v[146:147] offset:9216
	ds_write_b64 v127, v[162:163] offset:11520
	v_cvt_pk_bf16_f32 v146, v60, v61
	s_nop 1
	v_mov_b32_dpp v200, v0 quad_perm:[1,0,3,2] row_mask:0xf bank_mask:0xf
	v_perm_b32 v200, v200, v0, v195
	ds_write_b32 v229, v200 offset:18432
	s_nop 1
	v_mov_b32_dpp v228, v146 quad_perm:[1,0,3,2] row_mask:0xf bank_mask:0xf
	v_perm_b32 v228, v228, v146, v195
	ds_write_b32 v229, v228 offset:18720
	v_cvt_pk_bf16_f32 v0, v62, v63
	v_cvt_pk_bf16_f32 v146, v64, v65
	s_nop 1
	v_mov_b32_dpp v200, v0 quad_perm:[1,0,3,2] row_mask:0xf bank_mask:0xf
	v_perm_b32 v200, v200, v0, v195
	ds_write_b32 v229, v200 offset:18464
	s_nop 1
	v_mov_b32_dpp v228, v146 quad_perm:[1,0,3,2] row_mask:0xf bank_mask:0xf
	v_perm_b32 v228, v228, v146, v195
	ds_write_b32 v229, v228 offset:18752
	s_waitcnt lgkmcnt(0)
	s_barrier
	ds_read_b128 v[186:189], v69 offset:18432
	ds_read_b128 v[190:193], v118 offset:9216
	ds_read_b128 v[204:207], v118 offset:11520
	ds_read_b128 v[208:211], v69 offset:18496
	ds_read_b128 v[212:215], v118 offset:9280
	ds_read_b128 v[216:219], v118 offset:11584
	s_nop 0
	s_nop 0
	s_waitcnt lgkmcnt(4)
	v_mfma_f32_16x16x32_bf16 v[58:61], v[186:189], v[190:193], v[58:61]
	s_nop 0
	s_waitcnt lgkmcnt(3)
	v_mfma_f32_16x16x32_bf16 v[62:65], v[186:189], v[204:207], v[62:65]
	s_nop 0
	s_nop 0
	s_waitcnt lgkmcnt(1)
	v_mfma_f32_16x16x32_bf16 v[58:61], v[208:211], v[212:215], v[58:61]
	s_nop 0
	s_waitcnt lgkmcnt(0)
	v_mfma_f32_16x16x32_bf16 v[62:65], v[208:211], v[216:219], v[62:65]
	v_mov_b32_e32 v162, v208
	v_mov_b32_e32 v163, v209
	v_mov_b32_e32 v164, v210
	v_mov_b32_e32 v165, v211
	v_mov_b32_e32 v166, v216
	v_mov_b32_e32 v167, v217
	v_mov_b32_e32 v168, v218
	v_mov_b32_e32 v169, v219
	s_nop 4
	v_cvt_pk_bf16_f32 v0, v58, v59
	v_cvt_pk_bf16_f32 v58, v60, v61
	s_nop 1
	v_mov_b32_dpp v200, v0 quad_perm:[1,0,3,2] row_mask:0xf bank_mask:0xf
	v_perm_b32 v200, v200, v0, v195
	ds_write_b32 v229, v200 offset:27648
	s_nop 1
	v_mov_b32_dpp v228, v58 quad_perm:[1,0,3,2] row_mask:0xf bank_mask:0xf
	v_perm_b32 v228, v228, v58, v195
	ds_write_b32 v229, v228 offset:27936
	v_cvt_pk_bf16_f32 v0, v62, v63
	v_cvt_pk_bf16_f32 v58, v64, v65
	s_nop 1
	v_mov_b32_dpp v200, v0 quad_perm:[1,0,3,2] row_mask:0xf bank_mask:0xf
	v_perm_b32 v200, v200, v0, v195
	ds_write_b32 v229, v200 offset:27680
	s_nop 1
	v_mov_b32_dpp v228, v58 quad_perm:[1,0,3,2] row_mask:0xf bank_mask:0xf
	v_perm_b32 v228, v228, v58, v195
	ds_write_b32 v229, v228 offset:27968
	v_mfma_f32_16x16x32_bf16 v[42:45], v[22:25], v[42:45], 0
	s_waitcnt lgkmcnt(0)
	s_barrier
	v_mfma_f32_16x16x32_bf16 v[58:61], v[22:25], v[46:49], 0
	v_mfma_f32_16x16x32_bf16 v[38:41], v[22:25], v[38:41], 0
	v_mfma_f32_16x16x32_bf16 v[34:37], v[22:25], v[34:37], 0
	v_mfma_f32_16x16x32_bf16 v[46:49], v[18:21], v[54:57], v[42:45]
	v_mfma_f32_16x16x32_bf16 v[42:45], v[18:21], v[50:53], v[58:61]
	v_mfma_f32_16x16x32_bf16 v[22:25], v[18:21], v[30:33], v[38:41]
	v_mfma_f32_16x16x32_bf16 v[18:21], v[18:21], v[26:29], v[34:37]
	s_and_saveexec_b64 s[12:13], vcc
	s_cbranch_execz .LBB0_245
	ds_read_b128 v[26:29], v68 offset:27648
	s_waitcnt lgkmcnt(0)
	global_store_dwordx4 v[100:101], v[26:29], off
